# attention: check-free fast trip loops (while at least four tiles remain) in front of the existing loops, which now only run the last trips; far-branch islands for the grown code
# baseline (speedup 1.0000x reference)
.LBB0_228:
	s_and_b64 vcc, exec, s[16:17]
	s_cbranch_vccnz .LA_entry
	s_add_i32 s86, s9, 1
	s_add_i32 s87, s66, -1
	s_sub_u32 s80, s80, 0x20000
	s_subb_u32 s81, s81, 0
	s_add_i32 s5, s32, 0x16400
	s_add_i32 s28, s32, 0xc400
	s_add_i32 s29, s32, 0x11400
	s_cmp_eq_u32 s56, 0
	s_cselect_b32 s5, 0x4000, s5
	s_cselect_b32 s28, 0x8400, s28
	s_cselect_b32 s29, 0x24400, s29
	s_add_i32 s69, s66, -4
.LBF1_top:
	s_cmp_ge_i32 s65, s69
	s_cbranch_scc1 .LB1_top
	s_mov_b32 m0, s32
	s_add_u32 s80, s80, 0x20000
	s_addc_u32 s81, s81, 0
	global_load_lds_dwordx4 v128, s[80:81]
	s_add_i32 m0, m0, 0x2000
	s_nop 0
	global_load_lds_dwordx4 v129, s[80:81]
	s_add_i32 m0, s32, 0x12800
	s_nop 0
	global_load_lds_dwordx4 v130, s[80:81]
	s_add_i32 m0, m0, 0x2000
	s_nop 0
	global_load_lds_dwordx4 v131, s[80:81]
	s_mov_b32 m0, s5
	s_nop 0
	global_load_lds_dwordx4 v132, s[80:81]
	v_max_f32_e32 v176, v96, v80
	v_max3_f32 v177, v81, v98, v82
	v_max3_f32 v176, v176, v97, v99
	v_max3_f32 v177, v177, v100, v84
	v_max3_f32 v176, v176, v83, v101
	v_max3_f32 v177, v177, v102, v86
	v_max3_f32 v176, v176, v85, v103
	v_max3_f32 v177, v177, v104, v88
	v_max3_f32 v176, v176, v87, v105
	v_max3_f32 v177, v177, v106, v90
	v_max3_f32 v176, v176, v89, v107
	v_max3_f32 v177, v177, v108, v92
	v_max3_f32 v176, v176, v91, v109
	v_max3_f32 v177, v177, v110, v94
	v_max3_f32 v176, v176, v93, v111
	v_max3_f32 v176, v176, v95, v177
	v_mov_b32_e32 v177, v176
	s_nop 1
	v_permlane32_swap_b32_e32 v176, v177
	v_max_f32_e32 v176, v176, v177
	v_cmp_lt_f32_e32 vcc, 0x41000000, v176
	s_cbranch_vccnz .Lrs_bf1
.Latt_bf1_exp:
	v_exp_f32_e32 v96, v96
	v_exp_f32_e32 v97, v97
	v_exp_f32_e32 v176, v80
	v_exp_f32_e32 v177, v81
	v_exp_f32_e32 v98, v98
	v_exp_f32_e32 v99, v99
	v_exp_f32_e32 v178, v82
	v_exp_f32_e32 v179, v83
	v_exp_f32_e32 v100, v100
	v_exp_f32_e32 v101, v101
	v_exp_f32_e32 v180, v84
	v_exp_f32_e32 v181, v85
	v_exp_f32_e32 v102, v102
	v_exp_f32_e32 v103, v103
	v_exp_f32_e32 v182, v86
	v_exp_f32_e32 v183, v87
	v_exp_f32_e32 v104, v104
	v_exp_f32_e32 v105, v105
	v_exp_f32_e32 v184, v88
	v_exp_f32_e32 v185, v89
	v_exp_f32_e32 v106, v106
	v_exp_f32_e32 v107, v107
	v_exp_f32_e32 v186, v90
	v_exp_f32_e32 v187, v91
	v_exp_f32_e32 v108, v108
	v_exp_f32_e32 v109, v109
	v_exp_f32_e32 v188, v92
	v_exp_f32_e32 v189, v93
	v_exp_f32_e32 v110, v110
	v_exp_f32_e32 v111, v111
	v_exp_f32_e32 v190, v94
	v_exp_f32_e32 v191, v95
	v_cvt_pk_bf16_f32 v80, v96, v97
	v_cvt_pk_bf16_f32 v81, v98, v99
	v_cvt_pk_bf16_f32 v82, v100, v101
	v_cvt_pk_bf16_f32 v83, v102, v103
	v_cvt_pk_bf16_f32 v84, v104, v105
	v_cvt_pk_bf16_f32 v85, v106, v107
	v_cvt_pk_bf16_f32 v86, v108, v109
	v_cvt_pk_bf16_f32 v87, v110, v111
	v_cvt_pk_bf16_f32 v88, v176, v177
	v_cvt_pk_bf16_f32 v89, v178, v179
	v_cvt_pk_bf16_f32 v90, v180, v181
	v_cvt_pk_bf16_f32 v91, v182, v183
	v_cvt_pk_bf16_f32 v92, v184, v185
	v_cvt_pk_bf16_f32 v93, v186, v187
	v_cvt_pk_bf16_f32 v94, v188, v189
	v_cvt_pk_bf16_f32 v95, v190, v191
	v_pk_add_f32 v[96:97], v[96:97], v[100:101]
	v_pk_add_f32 v[98:99], v[98:99], v[102:103]
	v_pk_add_f32 v[176:177], v[176:177], v[180:181]
	v_pk_add_f32 v[178:179], v[178:179], v[182:183]
	v_pk_add_f32 v[96:97], v[96:97], v[104:105]
	v_pk_add_f32 v[98:99], v[98:99], v[106:107]
	v_pk_add_f32 v[176:177], v[176:177], v[184:185]
	v_pk_add_f32 v[178:179], v[178:179], v[186:187]
	v_pk_add_f32 v[96:97], v[96:97], v[108:109]
	v_pk_add_f32 v[98:99], v[98:99], v[110:111]
	v_pk_add_f32 v[176:177], v[176:177], v[188:189]
	v_pk_add_f32 v[178:179], v[178:179], v[190:191]
	v_pk_add_f32 v[96:97], v[96:97], v[98:99]
	v_pk_add_f32 v[176:177], v[176:177], v[178:179]
	s_nop 0
	v_pk_add_f32 v[96:97], v[96:97], v[176:177]
	s_nop 0
	v_add_f32_e32 v96, v96, v97
	v_add_f32_e32 v172, v172, v96
	v_add_u32_e32 v205, 0x5000, v165
	v_add_u32_e32 v206, 0x20400, v192
	s_waitcnt vmcnt(5) lgkmcnt(0)
	s_barrier
	ds_read_b64_tr_b16 v[96:97], v205 offset:34816
	ds_read_b64_tr_b16 v[98:99], v205 offset:37376
	ds_read_b64_tr_b16 v[100:101], v205 offset:39936
	ds_read_b64_tr_b16 v[102:103], v205 offset:42496
	ds_read_b64_tr_b16 v[104:105], v205 offset:45056
	ds_read_b64_tr_b16 v[106:107], v205 offset:47616
	ds_read_b64_tr_b16 v[108:109], v205 offset:50176
	ds_read_b64_tr_b16 v[110:111], v205 offset:52736
	ds_read_b64_tr_b16 v[176:177], v205 offset:34880
	ds_read_b64_tr_b16 v[178:179], v205 offset:37440
	ds_read_b64_tr_b16 v[180:181], v205 offset:40000
	ds_read_b64_tr_b16 v[182:183], v205 offset:42560
	ds_read_b64_tr_b16 v[184:185], v205 offset:45120
	ds_read_b64_tr_b16 v[186:187], v205 offset:47680
	s_setprio 1
	s_waitcnt lgkmcnt(12)
	v_mfma_f32_32x32x16_bf16 v[32:47], v[96:99], v[80:83], v[32:47]
	ds_read_b64_tr_b16 v[96:97], v205 offset:50240
	ds_read_b64_tr_b16 v[98:99], v205 offset:52800
	s_waitcnt lgkmcnt(12)
	v_mfma_f32_32x32x16_bf16 v[32:47], v[100:103], v[84:87], v[32:47]
	ds_read_b64_tr_b16 v[100:101], v205 offset:34944
	ds_read_b64_tr_b16 v[102:103], v205 offset:37504
	s_waitcnt lgkmcnt(12)
	v_mfma_f32_32x32x16_bf16 v[32:47], v[104:107], v[88:91], v[32:47]
	ds_read_b64_tr_b16 v[104:105], v205 offset:40064
	ds_read_b64_tr_b16 v[106:107], v205 offset:42624
	s_waitcnt lgkmcnt(12)
	v_mfma_f32_32x32x16_bf16 v[32:47], v[108:111], v[92:95], v[32:47]
	ds_read_b64_tr_b16 v[108:109], v205 offset:45184
	ds_read_b64_tr_b16 v[110:111], v205 offset:47744
	s_waitcnt lgkmcnt(12)
	v_mfma_f32_32x32x16_bf16 v[16:31], v[176:179], v[80:83], v[16:31]
	ds_read_b64_tr_b16 v[176:177], v205 offset:50304
	ds_read_b64_tr_b16 v[178:179], v205 offset:52864
	s_waitcnt lgkmcnt(12)
	v_mfma_f32_32x32x16_bf16 v[16:31], v[180:183], v[84:87], v[16:31]
	ds_read_b64_tr_b16 v[180:181], v205 offset:35008
	ds_read_b64_tr_b16 v[182:183], v205 offset:37568
	s_waitcnt lgkmcnt(12)
	v_mfma_f32_32x32x16_bf16 v[16:31], v[184:187], v[88:91], v[16:31]
	ds_read_b64_tr_b16 v[184:185], v205 offset:40128
	ds_read_b64_tr_b16 v[186:187], v205 offset:42688
	s_waitcnt lgkmcnt(12)
	v_mfma_f32_32x32x16_bf16 v[16:31], v[96:99], v[92:95], v[16:31]
	ds_read_b64_tr_b16 v[96:97], v205 offset:45248
	ds_read_b64_tr_b16 v[98:99], v205 offset:47808
	s_waitcnt lgkmcnt(12)
	v_mfma_f32_32x32x16_bf16 v[0:15], v[100:103], v[80:83], v[0:15]
	ds_read_b64_tr_b16 v[100:101], v205 offset:50368
	ds_read_b64_tr_b16 v[102:103], v205 offset:52928
	s_waitcnt lgkmcnt(12)
	v_mfma_f32_32x32x16_bf16 v[0:15], v[104:107], v[84:87], v[0:15]
	ds_read_b128 v[210:213], v206 offset:8704
	ds_read_b128 v[104:107], v206 offset:8736
	s_waitcnt lgkmcnt(12)
	v_mfma_f32_32x32x16_bf16 v[0:15], v[108:111], v[88:91], v[0:15]
	ds_read_b128 v[108:111], v206 offset:8768
	ds_read_b128 v[188:191], v206
	s_waitcnt lgkmcnt(12)
	v_mfma_f32_32x32x16_bf16 v[0:15], v[176:179], v[92:95], v[0:15]
	ds_read_b128 v[176:179], v206 offset:8800
	ds_read_b128 v[224:227], v206 offset:32
	s_waitcnt lgkmcnt(12)
	v_mfma_f32_32x32x16_bf16 v[48:63], v[180:183], v[80:83], v[48:63]
	ds_read_b128 v[228:231], v206 offset:64
	ds_read_b128 v[248:251], v206 offset:96
	s_waitcnt lgkmcnt(12)
	v_mfma_f32_32x32x16_bf16 v[48:63], v[184:187], v[84:87], v[48:63]
	s_waitcnt lgkmcnt(10)
	v_mfma_f32_32x32x16_bf16 v[48:63], v[96:99], v[88:91], v[48:63]
	s_waitcnt lgkmcnt(8)
	v_mfma_f32_32x32x16_bf16 v[48:63], v[100:103], v[92:95], v[48:63]
	s_waitcnt lgkmcnt(7)
	v_mfma_f32_32x32x16_bf16 v[80:95], v[210:213], v[112:115], v[64:79]
	s_waitcnt lgkmcnt(6)
	v_mfma_f32_32x32x16_bf16 v[80:95], v[104:107], v[116:119], v[80:95]
	s_waitcnt lgkmcnt(5)
	v_mfma_f32_32x32x16_bf16 v[80:95], v[108:111], v[120:123], v[80:95]
	s_waitcnt lgkmcnt(3)
	v_mfma_f32_32x32x16_bf16 v[80:95], v[176:179], v[124:127], v[80:95]
	s_waitcnt lgkmcnt(4)
	v_mfma_f32_32x32x16_bf16 v[96:111], v[188:191], v[112:115], v[64:79]
	s_waitcnt lgkmcnt(2)
	v_mfma_f32_32x32x16_bf16 v[96:111], v[224:227], v[116:119], v[96:111]
	s_waitcnt lgkmcnt(1)
	v_mfma_f32_32x32x16_bf16 v[96:111], v[228:231], v[120:123], v[96:111]
	s_waitcnt lgkmcnt(0)
	v_mfma_f32_32x32x16_bf16 v[96:111], v[248:251], v[124:127], v[96:111]
	s_setprio 0
	s_add_i32 s65, s65, 1
	s_add_i32 s33, s33, -1
.LBF2_top:
	s_cmp_ge_i32 s65, s69
	s_cbranch_scc1 .LB2_top
	s_add_i32 m0, s32, 0x4400
	s_add_u32 s80, s80, 0x20000
	s_addc_u32 s81, s81, 0
	global_load_lds_dwordx4 v128, s[80:81]
	s_add_i32 m0, m0, 0x2000
	s_nop 0
	global_load_lds_dwordx4 v129, s[80:81]
	s_add_i32 m0, s32, 0x8800
	s_nop 0
	global_load_lds_dwordx4 v130, s[80:81]
	s_add_i32 m0, m0, 0x2000
	s_nop 0
	global_load_lds_dwordx4 v131, s[80:81]
	s_mov_b32 m0, s28
	s_nop 0
	global_load_lds_dwordx4 v132, s[80:81]
	v_max_f32_e32 v176, v96, v80
	v_max3_f32 v177, v81, v98, v82
	v_max3_f32 v176, v176, v97, v99
	v_max3_f32 v177, v177, v100, v84
	v_max3_f32 v176, v176, v83, v101
	v_max3_f32 v177, v177, v102, v86
	v_max3_f32 v176, v176, v85, v103
	v_max3_f32 v177, v177, v104, v88
	v_max3_f32 v176, v176, v87, v105
	v_max3_f32 v177, v177, v106, v90
	v_max3_f32 v176, v176, v89, v107
	v_max3_f32 v177, v177, v108, v92
	v_max3_f32 v176, v176, v91, v109
	v_max3_f32 v177, v177, v110, v94
	v_max3_f32 v176, v176, v93, v111
	v_max3_f32 v176, v176, v95, v177
	v_mov_b32_e32 v177, v176
	s_nop 1
	v_permlane32_swap_b32_e32 v176, v177
	v_max_f32_e32 v176, v176, v177
	v_cmp_lt_f32_e32 vcc, 0x41000000, v176
	s_cbranch_vccnz .Lrs_bf2
.Latt_bf2_exp:
	v_exp_f32_e32 v96, v96
	v_exp_f32_e32 v97, v97
	v_exp_f32_e32 v176, v80
	v_exp_f32_e32 v177, v81
	v_exp_f32_e32 v98, v98
	v_exp_f32_e32 v99, v99
	v_exp_f32_e32 v178, v82
	v_exp_f32_e32 v179, v83
	v_exp_f32_e32 v100, v100
	v_exp_f32_e32 v101, v101
	v_exp_f32_e32 v180, v84
	v_exp_f32_e32 v181, v85
	v_exp_f32_e32 v102, v102
	v_exp_f32_e32 v103, v103
	v_exp_f32_e32 v182, v86
	v_exp_f32_e32 v183, v87
	v_exp_f32_e32 v104, v104
	v_exp_f32_e32 v105, v105
	v_exp_f32_e32 v184, v88
	v_exp_f32_e32 v185, v89
	v_exp_f32_e32 v106, v106
	v_exp_f32_e32 v107, v107
	v_exp_f32_e32 v186, v90
	v_exp_f32_e32 v187, v91
	v_exp_f32_e32 v108, v108
	v_exp_f32_e32 v109, v109
	v_exp_f32_e32 v188, v92
	v_exp_f32_e32 v189, v93
	v_exp_f32_e32 v110, v110
	v_exp_f32_e32 v111, v111
	v_exp_f32_e32 v190, v94
	v_exp_f32_e32 v191, v95
	v_cvt_pk_bf16_f32 v80, v96, v97
	v_cvt_pk_bf16_f32 v81, v98, v99
	v_cvt_pk_bf16_f32 v82, v100, v101
	v_cvt_pk_bf16_f32 v83, v102, v103
	v_cvt_pk_bf16_f32 v84, v104, v105
	v_cvt_pk_bf16_f32 v85, v106, v107
	v_cvt_pk_bf16_f32 v86, v108, v109
	v_cvt_pk_bf16_f32 v87, v110, v111
	v_cvt_pk_bf16_f32 v88, v176, v177
	v_cvt_pk_bf16_f32 v89, v178, v179
	v_cvt_pk_bf16_f32 v90, v180, v181
	v_cvt_pk_bf16_f32 v91, v182, v183
	v_cvt_pk_bf16_f32 v92, v184, v185
	v_cvt_pk_bf16_f32 v93, v186, v187
	v_cvt_pk_bf16_f32 v94, v188, v189
	v_cvt_pk_bf16_f32 v95, v190, v191
	v_pk_add_f32 v[96:97], v[96:97], v[100:101]
	v_pk_add_f32 v[98:99], v[98:99], v[102:103]
	v_pk_add_f32 v[176:177], v[176:177], v[180:181]
	v_pk_add_f32 v[178:179], v[178:179], v[182:183]
	v_pk_add_f32 v[96:97], v[96:97], v[104:105]
	v_pk_add_f32 v[98:99], v[98:99], v[106:107]
	v_pk_add_f32 v[176:177], v[176:177], v[184:185]
	v_pk_add_f32 v[178:179], v[178:179], v[186:187]
	v_pk_add_f32 v[96:97], v[96:97], v[108:109]
	v_pk_add_f32 v[98:99], v[98:99], v[110:111]
	v_pk_add_f32 v[176:177], v[176:177], v[188:189]
	v_pk_add_f32 v[178:179], v[178:179], v[190:191]
	v_pk_add_f32 v[96:97], v[96:97], v[98:99]
	v_pk_add_f32 v[176:177], v[176:177], v[178:179]
	s_nop 0
	v_pk_add_f32 v[96:97], v[96:97], v[176:177]
	s_nop 0
	v_add_f32_e32 v96, v96, v97
	v_add_f32_e32 v172, v172, v96
	v_add_u32_e32 v205, 0xa000, v165
	v_add_u32_e32 v206, 0x0, v192
	s_waitcnt vmcnt(5) lgkmcnt(0)
	s_barrier
	ds_read_b64_tr_b16 v[96:97], v205 offset:34816
	ds_read_b64_tr_b16 v[98:99], v205 offset:37376
	ds_read_b64_tr_b16 v[100:101], v205 offset:39936
	ds_read_b64_tr_b16 v[102:103], v205 offset:42496
	ds_read_b64_tr_b16 v[104:105], v205 offset:45056
	ds_read_b64_tr_b16 v[106:107], v205 offset:47616
	ds_read_b64_tr_b16 v[108:109], v205 offset:50176
	ds_read_b64_tr_b16 v[110:111], v205 offset:52736
	ds_read_b64_tr_b16 v[176:177], v205 offset:34880
	ds_read_b64_tr_b16 v[178:179], v205 offset:37440
	ds_read_b64_tr_b16 v[180:181], v205 offset:40000
	ds_read_b64_tr_b16 v[182:183], v205 offset:42560
	ds_read_b64_tr_b16 v[184:185], v205 offset:45120
	ds_read_b64_tr_b16 v[186:187], v205 offset:47680
	s_setprio 1
	s_waitcnt lgkmcnt(12)
	v_mfma_f32_32x32x16_bf16 v[32:47], v[96:99], v[80:83], v[32:47]
	ds_read_b64_tr_b16 v[96:97], v205 offset:50240
	ds_read_b64_tr_b16 v[98:99], v205 offset:52800
	s_waitcnt lgkmcnt(12)
	v_mfma_f32_32x32x16_bf16 v[32:47], v[100:103], v[84:87], v[32:47]
	ds_read_b64_tr_b16 v[100:101], v205 offset:34944
	ds_read_b64_tr_b16 v[102:103], v205 offset:37504
	s_waitcnt lgkmcnt(12)
	v_mfma_f32_32x32x16_bf16 v[32:47], v[104:107], v[88:91], v[32:47]
	ds_read_b64_tr_b16 v[104:105], v205 offset:40064
	ds_read_b64_tr_b16 v[106:107], v205 offset:42624
	s_waitcnt lgkmcnt(12)
	v_mfma_f32_32x32x16_bf16 v[32:47], v[108:111], v[92:95], v[32:47]
	ds_read_b64_tr_b16 v[108:109], v205 offset:45184
	ds_read_b64_tr_b16 v[110:111], v205 offset:47744
	s_waitcnt lgkmcnt(12)
	v_mfma_f32_32x32x16_bf16 v[16:31], v[176:179], v[80:83], v[16:31]
	ds_read_b64_tr_b16 v[176:177], v205 offset:50304
	ds_read_b64_tr_b16 v[178:179], v205 offset:52864
	s_waitcnt lgkmcnt(12)
	v_mfma_f32_32x32x16_bf16 v[16:31], v[180:183], v[84:87], v[16:31]
	ds_read_b64_tr_b16 v[180:181], v205 offset:35008
	ds_read_b64_tr_b16 v[182:183], v205 offset:37568
	s_waitcnt lgkmcnt(12)
	v_mfma_f32_32x32x16_bf16 v[16:31], v[184:187], v[88:91], v[16:31]
	ds_read_b64_tr_b16 v[184:185], v205 offset:40128
	ds_read_b64_tr_b16 v[186:187], v205 offset:42688
	s_waitcnt lgkmcnt(12)
	v_mfma_f32_32x32x16_bf16 v[16:31], v[96:99], v[92:95], v[16:31]
	ds_read_b64_tr_b16 v[96:97], v205 offset:45248
	ds_read_b64_tr_b16 v[98:99], v205 offset:47808
	s_waitcnt lgkmcnt(12)
	v_mfma_f32_32x32x16_bf16 v[0:15], v[100:103], v[80:83], v[0:15]
	ds_read_b64_tr_b16 v[100:101], v205 offset:50368
	ds_read_b64_tr_b16 v[102:103], v205 offset:52928
	s_waitcnt lgkmcnt(12)
	v_mfma_f32_32x32x16_bf16 v[0:15], v[104:107], v[84:87], v[0:15]
	ds_read_b128 v[210:213], v206 offset:8704
	ds_read_b128 v[104:107], v206 offset:8736
	s_waitcnt lgkmcnt(12)
	v_mfma_f32_32x32x16_bf16 v[0:15], v[108:111], v[88:91], v[0:15]
	ds_read_b128 v[108:111], v206 offset:8768
	ds_read_b128 v[188:191], v206
	s_waitcnt lgkmcnt(12)
	v_mfma_f32_32x32x16_bf16 v[0:15], v[176:179], v[92:95], v[0:15]
	ds_read_b128 v[176:179], v206 offset:8800
	ds_read_b128 v[224:227], v206 offset:32
	s_waitcnt lgkmcnt(12)
	v_mfma_f32_32x32x16_bf16 v[48:63], v[180:183], v[80:83], v[48:63]
	ds_read_b128 v[228:231], v206 offset:64
	ds_read_b128 v[248:251], v206 offset:96
	s_waitcnt lgkmcnt(12)
	v_mfma_f32_32x32x16_bf16 v[48:63], v[184:187], v[84:87], v[48:63]
	s_waitcnt lgkmcnt(10)
	v_mfma_f32_32x32x16_bf16 v[48:63], v[96:99], v[88:91], v[48:63]
	s_waitcnt lgkmcnt(8)
	v_mfma_f32_32x32x16_bf16 v[48:63], v[100:103], v[92:95], v[48:63]
	s_waitcnt lgkmcnt(7)
	v_mfma_f32_32x32x16_bf16 v[80:95], v[210:213], v[112:115], v[64:79]
	s_waitcnt lgkmcnt(6)
	v_mfma_f32_32x32x16_bf16 v[80:95], v[104:107], v[116:119], v[80:95]
	s_waitcnt lgkmcnt(5)
	v_mfma_f32_32x32x16_bf16 v[80:95], v[108:111], v[120:123], v[80:95]
	s_waitcnt lgkmcnt(3)
	v_mfma_f32_32x32x16_bf16 v[80:95], v[176:179], v[124:127], v[80:95]
	s_waitcnt lgkmcnt(4)
	v_mfma_f32_32x32x16_bf16 v[96:111], v[188:191], v[112:115], v[64:79]
	s_waitcnt lgkmcnt(2)
	v_mfma_f32_32x32x16_bf16 v[96:111], v[224:227], v[116:119], v[96:111]
	s_waitcnt lgkmcnt(1)
	v_mfma_f32_32x32x16_bf16 v[96:111], v[228:231], v[120:123], v[96:111]
	s_waitcnt lgkmcnt(0)
	v_mfma_f32_32x32x16_bf16 v[96:111], v[248:251], v[124:127], v[96:111]
	s_setprio 0
	s_add_i32 s65, s65, 1
	s_add_i32 s33, s33, -1
.LBF0_top:
	s_cmp_ge_i32 s65, s69
	s_cbranch_scc1 .LB0_top
	s_add_i32 m0, s32, 0x20400
	s_add_u32 s80, s80, 0x20000
	s_addc_u32 s81, s81, 0
	global_load_lds_dwordx4 v128, s[80:81]
	s_add_i32 m0, m0, 0x2000
	s_nop 0
	global_load_lds_dwordx4 v129, s[80:81]
	s_add_i32 m0, s32, 0xd800
	s_nop 0
	global_load_lds_dwordx4 v130, s[80:81]
	s_add_i32 m0, m0, 0x2000
	s_nop 0
	global_load_lds_dwordx4 v131, s[80:81]
	s_mov_b32 m0, s29
	s_nop 0
	global_load_lds_dwordx4 v132, s[80:81]
	v_max_f32_e32 v176, v96, v80
	v_max3_f32 v177, v81, v98, v82
	v_max3_f32 v176, v176, v97, v99
	v_max3_f32 v177, v177, v100, v84
	v_max3_f32 v176, v176, v83, v101
	v_max3_f32 v177, v177, v102, v86
	v_max3_f32 v176, v176, v85, v103
	v_max3_f32 v177, v177, v104, v88
	v_max3_f32 v176, v176, v87, v105
	v_max3_f32 v177, v177, v106, v90
	v_max3_f32 v176, v176, v89, v107
	v_max3_f32 v177, v177, v108, v92
	v_max3_f32 v176, v176, v91, v109
	v_max3_f32 v177, v177, v110, v94
	v_max3_f32 v176, v176, v93, v111
	v_max3_f32 v176, v176, v95, v177
	v_mov_b32_e32 v177, v176
	s_nop 1
	v_permlane32_swap_b32_e32 v176, v177
	v_max_f32_e32 v176, v176, v177
	v_cmp_lt_f32_e32 vcc, 0x41000000, v176
	s_cbranch_vccnz .Lrs_bf0
.Latt_bf0_exp:
	v_exp_f32_e32 v96, v96
	v_exp_f32_e32 v97, v97
	v_exp_f32_e32 v176, v80
	v_exp_f32_e32 v177, v81
	v_exp_f32_e32 v98, v98
	v_exp_f32_e32 v99, v99
	v_exp_f32_e32 v178, v82
	v_exp_f32_e32 v179, v83
	v_exp_f32_e32 v100, v100
	v_exp_f32_e32 v101, v101
	v_exp_f32_e32 v180, v84
	v_exp_f32_e32 v181, v85
	v_exp_f32_e32 v102, v102
	v_exp_f32_e32 v103, v103
	v_exp_f32_e32 v182, v86
	v_exp_f32_e32 v183, v87
	v_exp_f32_e32 v104, v104
	v_exp_f32_e32 v105, v105
	v_exp_f32_e32 v184, v88
	v_exp_f32_e32 v185, v89
	v_exp_f32_e32 v106, v106
	v_exp_f32_e32 v107, v107
	v_exp_f32_e32 v186, v90
	v_exp_f32_e32 v187, v91
	v_exp_f32_e32 v108, v108
	v_exp_f32_e32 v109, v109
	v_exp_f32_e32 v188, v92
	v_exp_f32_e32 v189, v93
	v_exp_f32_e32 v110, v110
	v_exp_f32_e32 v111, v111
	v_exp_f32_e32 v190, v94
	v_exp_f32_e32 v191, v95
	v_cvt_pk_bf16_f32 v80, v96, v97
	v_cvt_pk_bf16_f32 v81, v98, v99
	v_cvt_pk_bf16_f32 v82, v100, v101
	v_cvt_pk_bf16_f32 v83, v102, v103
	v_cvt_pk_bf16_f32 v84, v104, v105
	v_cvt_pk_bf16_f32 v85, v106, v107
	v_cvt_pk_bf16_f32 v86, v108, v109
	v_cvt_pk_bf16_f32 v87, v110, v111
	v_cvt_pk_bf16_f32 v88, v176, v177
	v_cvt_pk_bf16_f32 v89, v178, v179
	v_cvt_pk_bf16_f32 v90, v180, v181
	v_cvt_pk_bf16_f32 v91, v182, v183
	v_cvt_pk_bf16_f32 v92, v184, v185
	v_cvt_pk_bf16_f32 v93, v186, v187
	v_cvt_pk_bf16_f32 v94, v188, v189
	v_cvt_pk_bf16_f32 v95, v190, v191
	v_pk_add_f32 v[96:97], v[96:97], v[100:101]
	v_pk_add_f32 v[98:99], v[98:99], v[102:103]
	v_pk_add_f32 v[176:177], v[176:177], v[180:181]
	v_pk_add_f32 v[178:179], v[178:179], v[182:183]
	v_pk_add_f32 v[96:97], v[96:97], v[104:105]
	v_pk_add_f32 v[98:99], v[98:99], v[106:107]
	v_pk_add_f32 v[176:177], v[176:177], v[184:185]
	v_pk_add_f32 v[178:179], v[178:179], v[186:187]
	v_pk_add_f32 v[96:97], v[96:97], v[108:109]
	v_pk_add_f32 v[98:99], v[98:99], v[110:111]
	v_pk_add_f32 v[176:177], v[176:177], v[188:189]
	v_pk_add_f32 v[178:179], v[178:179], v[190:191]
	v_pk_add_f32 v[96:97], v[96:97], v[98:99]
	v_pk_add_f32 v[176:177], v[176:177], v[178:179]
	s_nop 0
	v_pk_add_f32 v[96:97], v[96:97], v[176:177]
	s_nop 0
	v_add_f32_e32 v96, v96, v97
	v_add_f32_e32 v172, v172, v96
	v_add_u32_e32 v205, 0x0, v165
	v_add_u32_e32 v206, 0x4400, v192
	s_waitcnt vmcnt(5) lgkmcnt(0)
	s_barrier
	ds_read_b64_tr_b16 v[96:97], v205 offset:34816
	ds_read_b64_tr_b16 v[98:99], v205 offset:37376
	ds_read_b64_tr_b16 v[100:101], v205 offset:39936
	ds_read_b64_tr_b16 v[102:103], v205 offset:42496
	ds_read_b64_tr_b16 v[104:105], v205 offset:45056
	ds_read_b64_tr_b16 v[106:107], v205 offset:47616
	ds_read_b64_tr_b16 v[108:109], v205 offset:50176
	ds_read_b64_tr_b16 v[110:111], v205 offset:52736
	ds_read_b64_tr_b16 v[176:177], v205 offset:34880
	ds_read_b64_tr_b16 v[178:179], v205 offset:37440
	ds_read_b64_tr_b16 v[180:181], v205 offset:40000
	ds_read_b64_tr_b16 v[182:183], v205 offset:42560
	ds_read_b64_tr_b16 v[184:185], v205 offset:45120
	ds_read_b64_tr_b16 v[186:187], v205 offset:47680
	s_setprio 1
	s_waitcnt lgkmcnt(12)
	v_mfma_f32_32x32x16_bf16 v[32:47], v[96:99], v[80:83], v[32:47]
	ds_read_b64_tr_b16 v[96:97], v205 offset:50240
	ds_read_b64_tr_b16 v[98:99], v205 offset:52800
	s_waitcnt lgkmcnt(12)
	v_mfma_f32_32x32x16_bf16 v[32:47], v[100:103], v[84:87], v[32:47]
	ds_read_b64_tr_b16 v[100:101], v205 offset:34944
	ds_read_b64_tr_b16 v[102:103], v205 offset:37504
	s_waitcnt lgkmcnt(12)
	v_mfma_f32_32x32x16_bf16 v[32:47], v[104:107], v[88:91], v[32:47]
	ds_read_b64_tr_b16 v[104:105], v205 offset:40064
	ds_read_b64_tr_b16 v[106:107], v205 offset:42624
	s_waitcnt lgkmcnt(12)
	v_mfma_f32_32x32x16_bf16 v[32:47], v[108:111], v[92:95], v[32:47]
	ds_read_b64_tr_b16 v[108:109], v205 offset:45184
	ds_read_b64_tr_b16 v[110:111], v205 offset:47744
	s_waitcnt lgkmcnt(12)
	v_mfma_f32_32x32x16_bf16 v[16:31], v[176:179], v[80:83], v[16:31]
	ds_read_b64_tr_b16 v[176:177], v205 offset:50304
	ds_read_b64_tr_b16 v[178:179], v205 offset:52864
	s_waitcnt lgkmcnt(12)
	v_mfma_f32_32x32x16_bf16 v[16:31], v[180:183], v[84:87], v[16:31]
	ds_read_b64_tr_b16 v[180:181], v205 offset:35008
	ds_read_b64_tr_b16 v[182:183], v205 offset:37568
	s_waitcnt lgkmcnt(12)
	v_mfma_f32_32x32x16_bf16 v[16:31], v[184:187], v[88:91], v[16:31]
	ds_read_b64_tr_b16 v[184:185], v205 offset:40128
	ds_read_b64_tr_b16 v[186:187], v205 offset:42688
	s_waitcnt lgkmcnt(12)
	v_mfma_f32_32x32x16_bf16 v[16:31], v[96:99], v[92:95], v[16:31]
	ds_read_b64_tr_b16 v[96:97], v205 offset:45248
	ds_read_b64_tr_b16 v[98:99], v205 offset:47808
	s_waitcnt lgkmcnt(12)
	v_mfma_f32_32x32x16_bf16 v[0:15], v[100:103], v[80:83], v[0:15]
	ds_read_b64_tr_b16 v[100:101], v205 offset:50368
	ds_read_b64_tr_b16 v[102:103], v205 offset:52928
	s_waitcnt lgkmcnt(12)
	v_mfma_f32_32x32x16_bf16 v[0:15], v[104:107], v[84:87], v[0:15]
	ds_read_b128 v[210:213], v206 offset:8704
	ds_read_b128 v[104:107], v206 offset:8736
	s_waitcnt lgkmcnt(12)
	v_mfma_f32_32x32x16_bf16 v[0:15], v[108:111], v[88:91], v[0:15]
	ds_read_b128 v[108:111], v206 offset:8768
	ds_read_b128 v[188:191], v206
	s_waitcnt lgkmcnt(12)
	v_mfma_f32_32x32x16_bf16 v[0:15], v[176:179], v[92:95], v[0:15]
	ds_read_b128 v[176:179], v206 offset:8800
	ds_read_b128 v[224:227], v206 offset:32
	s_waitcnt lgkmcnt(12)
	v_mfma_f32_32x32x16_bf16 v[48:63], v[180:183], v[80:83], v[48:63]
	ds_read_b128 v[228:231], v206 offset:64
	ds_read_b128 v[248:251], v206 offset:96
	s_waitcnt lgkmcnt(12)
	v_mfma_f32_32x32x16_bf16 v[48:63], v[184:187], v[84:87], v[48:63]
	s_waitcnt lgkmcnt(10)
	v_mfma_f32_32x32x16_bf16 v[48:63], v[96:99], v[88:91], v[48:63]
	s_waitcnt lgkmcnt(8)
	v_mfma_f32_32x32x16_bf16 v[48:63], v[100:103], v[92:95], v[48:63]
	s_waitcnt lgkmcnt(7)
	v_mfma_f32_32x32x16_bf16 v[80:95], v[210:213], v[112:115], v[64:79]
	s_waitcnt lgkmcnt(6)
	v_mfma_f32_32x32x16_bf16 v[80:95], v[104:107], v[116:119], v[80:95]
	s_waitcnt lgkmcnt(5)
	v_mfma_f32_32x32x16_bf16 v[80:95], v[108:111], v[120:123], v[80:95]
	s_waitcnt lgkmcnt(3)
	v_mfma_f32_32x32x16_bf16 v[80:95], v[176:179], v[124:127], v[80:95]
	s_waitcnt lgkmcnt(4)
	v_mfma_f32_32x32x16_bf16 v[96:111], v[188:191], v[112:115], v[64:79]
	s_waitcnt lgkmcnt(2)
	v_mfma_f32_32x32x16_bf16 v[96:111], v[224:227], v[116:119], v[96:111]
	s_waitcnt lgkmcnt(1)
	v_mfma_f32_32x32x16_bf16 v[96:111], v[228:231], v[120:123], v[96:111]
	s_waitcnt lgkmcnt(0)
	v_mfma_f32_32x32x16_bf16 v[96:111], v[248:251], v[124:127], v[96:111]
	s_setprio 0
	s_add_i32 s65, s65, 1
	s_add_i32 s33, s33, -1
	s_branch .LBF1_top

.LA_entry:
	s_add_i32 s87, s66, -2
	s_add_i32 s5, s32, 0xc400
	s_add_i32 s28, s32, 0x11400
	s_add_i32 s29, s32, 0x16400
	s_add_i32 s69, s66, -4
.LAF1_top:
	s_cmp_ge_i32 s65, s69
	s_cbranch_scc1 .LA1_top
	v_add_u32_e32 v205, 0x0, v165
	v_add_u32_e32 v206, 0x4400, v192
	ds_read_b64_tr_b16 v[96:97], v205 offset:34816
	ds_read_b64_tr_b16 v[98:99], v205 offset:37376
	ds_read_b64_tr_b16 v[100:101], v205 offset:39936
	ds_read_b64_tr_b16 v[102:103], v205 offset:42496
	ds_read_b64_tr_b16 v[104:105], v205 offset:45056
	ds_read_b64_tr_b16 v[106:107], v205 offset:47616
	ds_read_b64_tr_b16 v[108:109], v205 offset:50176
	ds_read_b64_tr_b16 v[110:111], v205 offset:52736
	ds_read_b64_tr_b16 v[176:177], v205 offset:34880
	ds_read_b64_tr_b16 v[178:179], v205 offset:37440
	ds_read_b64_tr_b16 v[180:181], v205 offset:40000
	ds_read_b64_tr_b16 v[182:183], v205 offset:42560
	ds_read_b64_tr_b16 v[184:185], v205 offset:45120
	ds_read_b64_tr_b16 v[186:187], v205 offset:47680
	s_setprio 1
	s_waitcnt lgkmcnt(12)
	v_mfma_f32_32x32x16_bf16 v[32:47], v[96:99], v[80:83], v[32:47]
	ds_read_b64_tr_b16 v[96:97], v205 offset:50240
	ds_read_b64_tr_b16 v[98:99], v205 offset:52800
	s_waitcnt lgkmcnt(12)
	v_mfma_f32_32x32x16_bf16 v[32:47], v[100:103], v[84:87], v[32:47]
	ds_read_b64_tr_b16 v[100:101], v205 offset:34944
	ds_read_b64_tr_b16 v[102:103], v205 offset:37504
	s_waitcnt lgkmcnt(12)
	v_mfma_f32_32x32x16_bf16 v[32:47], v[104:107], v[88:91], v[32:47]
	ds_read_b64_tr_b16 v[104:105], v205 offset:40064
	ds_read_b64_tr_b16 v[106:107], v205 offset:42624
	s_waitcnt lgkmcnt(12)
	v_mfma_f32_32x32x16_bf16 v[32:47], v[108:111], v[92:95], v[32:47]
	ds_read_b64_tr_b16 v[108:109], v205 offset:45184
	ds_read_b64_tr_b16 v[110:111], v205 offset:47744
	s_waitcnt lgkmcnt(12)
	v_mfma_f32_32x32x16_bf16 v[16:31], v[176:179], v[80:83], v[16:31]
	ds_read_b64_tr_b16 v[176:177], v205 offset:50304
	ds_read_b64_tr_b16 v[178:179], v205 offset:52864
	s_waitcnt lgkmcnt(12)
	v_mfma_f32_32x32x16_bf16 v[16:31], v[180:183], v[84:87], v[16:31]
	ds_read_b64_tr_b16 v[180:181], v205 offset:35008
	ds_read_b64_tr_b16 v[182:183], v205 offset:37568
	s_waitcnt lgkmcnt(12)
	v_mfma_f32_32x32x16_bf16 v[16:31], v[184:187], v[88:91], v[16:31]
	ds_read_b64_tr_b16 v[184:185], v205 offset:40128
	ds_read_b64_tr_b16 v[186:187], v205 offset:42688
	s_waitcnt lgkmcnt(12)
	v_mfma_f32_32x32x16_bf16 v[16:31], v[96:99], v[92:95], v[16:31]
	ds_read_b64_tr_b16 v[96:97], v205 offset:45248
	ds_read_b64_tr_b16 v[98:99], v205 offset:47808
	s_waitcnt lgkmcnt(12)
	v_mfma_f32_32x32x16_bf16 v[0:15], v[100:103], v[80:83], v[0:15]
	ds_read_b64_tr_b16 v[100:101], v205 offset:50368
	ds_read_b64_tr_b16 v[102:103], v205 offset:52928
	s_waitcnt lgkmcnt(12)
	v_mfma_f32_32x32x16_bf16 v[0:15], v[104:107], v[84:87], v[0:15]
	ds_read_b128 v[210:213], v206 offset:8704
	ds_read_b128 v[104:107], v206 offset:8736
	s_waitcnt lgkmcnt(12)
	v_mfma_f32_32x32x16_bf16 v[0:15], v[108:111], v[88:91], v[0:15]
	ds_read_b128 v[108:111], v206 offset:8768
	ds_read_b128 v[188:191], v206
	s_waitcnt lgkmcnt(12)
	v_mfma_f32_32x32x16_bf16 v[0:15], v[176:179], v[92:95], v[0:15]
	ds_read_b128 v[176:179], v206 offset:8800
	ds_read_b128 v[224:227], v206 offset:32
	s_waitcnt lgkmcnt(12)
	v_mfma_f32_32x32x16_bf16 v[48:63], v[180:183], v[80:83], v[48:63]
	ds_read_b128 v[228:231], v206 offset:64
	ds_read_b128 v[248:251], v206 offset:96
	s_waitcnt lgkmcnt(12)
	v_mfma_f32_32x32x16_bf16 v[48:63], v[184:187], v[84:87], v[48:63]
	s_waitcnt lgkmcnt(10)
	v_mfma_f32_32x32x16_bf16 v[48:63], v[96:99], v[88:91], v[48:63]
	s_waitcnt lgkmcnt(8)
	v_mfma_f32_32x32x16_bf16 v[48:63], v[100:103], v[92:95], v[48:63]
	s_waitcnt lgkmcnt(7)
	v_mfma_f32_32x32x16_bf16 v[80:95], v[210:213], v[112:115], v[64:79]
	s_waitcnt lgkmcnt(6)
	v_mfma_f32_32x32x16_bf16 v[80:95], v[104:107], v[116:119], v[80:95]
	s_waitcnt lgkmcnt(5)
	v_mfma_f32_32x32x16_bf16 v[80:95], v[108:111], v[120:123], v[80:95]
	s_waitcnt lgkmcnt(3)
	v_mfma_f32_32x32x16_bf16 v[80:95], v[176:179], v[124:127], v[80:95]
	s_waitcnt lgkmcnt(4)
	v_mfma_f32_32x32x16_bf16 v[96:111], v[188:191], v[112:115], v[64:79]
	s_waitcnt lgkmcnt(2)
	v_mfma_f32_32x32x16_bf16 v[96:111], v[224:227], v[116:119], v[96:111]
	s_waitcnt lgkmcnt(1)
	v_mfma_f32_32x32x16_bf16 v[96:111], v[228:231], v[120:123], v[96:111]
	s_waitcnt lgkmcnt(0)
	v_mfma_f32_32x32x16_bf16 v[96:111], v[248:251], v[124:127], v[96:111]
	s_setprio 0
	s_cmp_eq_u32 s56, 4
	s_cbranch_scc1 .Lw5_af1
	s_waitcnt vmcnt(4) lgkmcnt(0)
.Lw5_af1:
	s_waitcnt vmcnt(5) lgkmcnt(0)
	s_barrier
	s_add_i32 m0, s32, 0x4400
	s_add_u32 s80, s80, 0x20000
	s_addc_u32 s81, s81, 0
	global_load_lds_dwordx4 v128, s[80:81]
	s_add_i32 m0, m0, 0x2000
	s_nop 0
	global_load_lds_dwordx4 v129, s[80:81]
	s_add_i32 m0, s32, 0x8800
	s_nop 0
	global_load_lds_dwordx4 v130, s[80:81]
	s_add_i32 m0, m0, 0x2000
	s_cmp_eq_u32 s56, 4
	global_load_lds_dwordx4 v131, s[80:81]
	s_cbranch_scc0 .Lnod_af1
	s_mov_b32 m0, s5
	s_nop 0
	global_load_lds_dwordx4 v132, s[80:81]

.Latt_af1_exp:
	v_exp_f32_e32 v96, v96
	v_exp_f32_e32 v97, v97
	v_exp_f32_e32 v176, v80
	v_exp_f32_e32 v177, v81
	v_exp_f32_e32 v98, v98
	v_exp_f32_e32 v99, v99
	v_exp_f32_e32 v178, v82
	v_exp_f32_e32 v179, v83
	v_exp_f32_e32 v100, v100
	v_exp_f32_e32 v101, v101
	v_exp_f32_e32 v180, v84
	v_exp_f32_e32 v181, v85
	v_exp_f32_e32 v102, v102
	v_exp_f32_e32 v103, v103
	v_exp_f32_e32 v182, v86
	v_exp_f32_e32 v183, v87
	v_exp_f32_e32 v104, v104
	v_exp_f32_e32 v105, v105
	v_exp_f32_e32 v184, v88
	v_exp_f32_e32 v185, v89
	v_exp_f32_e32 v106, v106
	v_exp_f32_e32 v107, v107
	v_exp_f32_e32 v186, v90
	v_exp_f32_e32 v187, v91
	v_exp_f32_e32 v108, v108
	v_exp_f32_e32 v109, v109
	v_exp_f32_e32 v188, v92
	v_exp_f32_e32 v189, v93
	v_exp_f32_e32 v110, v110
	v_exp_f32_e32 v111, v111
	v_exp_f32_e32 v190, v94
	v_exp_f32_e32 v191, v95
	v_cvt_pk_bf16_f32 v80, v96, v97
	v_cvt_pk_bf16_f32 v81, v98, v99
	v_cvt_pk_bf16_f32 v82, v100, v101
	v_cvt_pk_bf16_f32 v83, v102, v103
	v_cvt_pk_bf16_f32 v84, v104, v105
	v_cvt_pk_bf16_f32 v85, v106, v107
	v_cvt_pk_bf16_f32 v86, v108, v109
	v_cvt_pk_bf16_f32 v87, v110, v111
	v_cvt_pk_bf16_f32 v88, v176, v177
	v_cvt_pk_bf16_f32 v89, v178, v179
	v_cvt_pk_bf16_f32 v90, v180, v181
	v_cvt_pk_bf16_f32 v91, v182, v183
	v_cvt_pk_bf16_f32 v92, v184, v185
	v_cvt_pk_bf16_f32 v93, v186, v187
	v_cvt_pk_bf16_f32 v94, v188, v189
	v_cvt_pk_bf16_f32 v95, v190, v191
	v_pk_add_f32 v[96:97], v[96:97], v[100:101]
	v_pk_add_f32 v[98:99], v[98:99], v[102:103]
	v_pk_add_f32 v[176:177], v[176:177], v[180:181]
	v_pk_add_f32 v[178:179], v[178:179], v[182:183]
	v_pk_add_f32 v[96:97], v[96:97], v[104:105]
	v_pk_add_f32 v[98:99], v[98:99], v[106:107]
	v_pk_add_f32 v[176:177], v[176:177], v[184:185]
	v_pk_add_f32 v[178:179], v[178:179], v[186:187]
	v_pk_add_f32 v[96:97], v[96:97], v[108:109]
	v_pk_add_f32 v[98:99], v[98:99], v[110:111]
	v_pk_add_f32 v[176:177], v[176:177], v[188:189]
	v_pk_add_f32 v[178:179], v[178:179], v[190:191]
	v_pk_add_f32 v[96:97], v[96:97], v[98:99]
	v_pk_add_f32 v[176:177], v[176:177], v[178:179]
	s_nop 0
	v_pk_add_f32 v[96:97], v[96:97], v[176:177]
	s_nop 0
	v_add_f32_e32 v96, v96, v97
	v_add_f32_e32 v172, v172, v96
	s_add_i32 s65, s65, 1
	s_add_i32 s33, s33, -1
.LAF2_top:
	s_cmp_ge_i32 s65, s69
	s_cbranch_scc1 .LA2_top
	v_add_u32_e32 v205, 0x5000, v165
	v_add_u32_e32 v206, 0x20400, v192
	ds_read_b64_tr_b16 v[96:97], v205 offset:34816
	ds_read_b64_tr_b16 v[98:99], v205 offset:37376
	ds_read_b64_tr_b16 v[100:101], v205 offset:39936
	ds_read_b64_tr_b16 v[102:103], v205 offset:42496
	ds_read_b64_tr_b16 v[104:105], v205 offset:45056
	ds_read_b64_tr_b16 v[106:107], v205 offset:47616
	ds_read_b64_tr_b16 v[108:109], v205 offset:50176
	ds_read_b64_tr_b16 v[110:111], v205 offset:52736
	ds_read_b64_tr_b16 v[176:177], v205 offset:34880
	ds_read_b64_tr_b16 v[178:179], v205 offset:37440
	ds_read_b64_tr_b16 v[180:181], v205 offset:40000
	ds_read_b64_tr_b16 v[182:183], v205 offset:42560
	ds_read_b64_tr_b16 v[184:185], v205 offset:45120
	ds_read_b64_tr_b16 v[186:187], v205 offset:47680
	s_setprio 1
	s_waitcnt lgkmcnt(12)
	v_mfma_f32_32x32x16_bf16 v[32:47], v[96:99], v[80:83], v[32:47]
	ds_read_b64_tr_b16 v[96:97], v205 offset:50240
	ds_read_b64_tr_b16 v[98:99], v205 offset:52800
	s_waitcnt lgkmcnt(12)
	v_mfma_f32_32x32x16_bf16 v[32:47], v[100:103], v[84:87], v[32:47]
	ds_read_b64_tr_b16 v[100:101], v205 offset:34944
	ds_read_b64_tr_b16 v[102:103], v205 offset:37504
	s_waitcnt lgkmcnt(12)
	v_mfma_f32_32x32x16_bf16 v[32:47], v[104:107], v[88:91], v[32:47]
	ds_read_b64_tr_b16 v[104:105], v205 offset:40064
	ds_read_b64_tr_b16 v[106:107], v205 offset:42624
	s_waitcnt lgkmcnt(12)
	v_mfma_f32_32x32x16_bf16 v[32:47], v[108:111], v[92:95], v[32:47]
	ds_read_b64_tr_b16 v[108:109], v205 offset:45184
	ds_read_b64_tr_b16 v[110:111], v205 offset:47744
	s_waitcnt lgkmcnt(12)
	v_mfma_f32_32x32x16_bf16 v[16:31], v[176:179], v[80:83], v[16:31]
	ds_read_b64_tr_b16 v[176:177], v205 offset:50304
	ds_read_b64_tr_b16 v[178:179], v205 offset:52864
	s_waitcnt lgkmcnt(12)
	v_mfma_f32_32x32x16_bf16 v[16:31], v[180:183], v[84:87], v[16:31]
	ds_read_b64_tr_b16 v[180:181], v205 offset:35008
	ds_read_b64_tr_b16 v[182:183], v205 offset:37568
	s_waitcnt lgkmcnt(12)
	v_mfma_f32_32x32x16_bf16 v[16:31], v[184:187], v[88:91], v[16:31]
	ds_read_b64_tr_b16 v[184:185], v205 offset:40128
	ds_read_b64_tr_b16 v[186:187], v205 offset:42688
	s_waitcnt lgkmcnt(12)
	v_mfma_f32_32x32x16_bf16 v[16:31], v[96:99], v[92:95], v[16:31]
	ds_read_b64_tr_b16 v[96:97], v205 offset:45248
	ds_read_b64_tr_b16 v[98:99], v205 offset:47808
	s_waitcnt lgkmcnt(12)
	v_mfma_f32_32x32x16_bf16 v[0:15], v[100:103], v[80:83], v[0:15]
	ds_read_b64_tr_b16 v[100:101], v205 offset:50368
	ds_read_b64_tr_b16 v[102:103], v205 offset:52928
	s_waitcnt lgkmcnt(12)
	v_mfma_f32_32x32x16_bf16 v[0:15], v[104:107], v[84:87], v[0:15]
	ds_read_b128 v[210:213], v206 offset:8704
	ds_read_b128 v[104:107], v206 offset:8736
	s_waitcnt lgkmcnt(12)
	v_mfma_f32_32x32x16_bf16 v[0:15], v[108:111], v[88:91], v[0:15]
	ds_read_b128 v[108:111], v206 offset:8768
	ds_read_b128 v[188:191], v206
	s_waitcnt lgkmcnt(12)
	v_mfma_f32_32x32x16_bf16 v[0:15], v[176:179], v[92:95], v[0:15]
	ds_read_b128 v[176:179], v206 offset:8800
	ds_read_b128 v[224:227], v206 offset:32
	s_waitcnt lgkmcnt(12)
	v_mfma_f32_32x32x16_bf16 v[48:63], v[180:183], v[80:83], v[48:63]
	ds_read_b128 v[228:231], v206 offset:64
	ds_read_b128 v[248:251], v206 offset:96
	s_waitcnt lgkmcnt(12)
	v_mfma_f32_32x32x16_bf16 v[48:63], v[184:187], v[84:87], v[48:63]
	s_waitcnt lgkmcnt(10)
	v_mfma_f32_32x32x16_bf16 v[48:63], v[96:99], v[88:91], v[48:63]
	s_waitcnt lgkmcnt(8)
	v_mfma_f32_32x32x16_bf16 v[48:63], v[100:103], v[92:95], v[48:63]
	s_waitcnt lgkmcnt(7)
	v_mfma_f32_32x32x16_bf16 v[80:95], v[210:213], v[112:115], v[64:79]
	s_waitcnt lgkmcnt(6)
	v_mfma_f32_32x32x16_bf16 v[80:95], v[104:107], v[116:119], v[80:95]
	s_waitcnt lgkmcnt(5)
	v_mfma_f32_32x32x16_bf16 v[80:95], v[108:111], v[120:123], v[80:95]
	s_waitcnt lgkmcnt(3)
	v_mfma_f32_32x32x16_bf16 v[80:95], v[176:179], v[124:127], v[80:95]
	s_waitcnt lgkmcnt(4)
	v_mfma_f32_32x32x16_bf16 v[96:111], v[188:191], v[112:115], v[64:79]
	s_waitcnt lgkmcnt(2)
	v_mfma_f32_32x32x16_bf16 v[96:111], v[224:227], v[116:119], v[96:111]
	s_waitcnt lgkmcnt(1)
	v_mfma_f32_32x32x16_bf16 v[96:111], v[228:231], v[120:123], v[96:111]
	s_waitcnt lgkmcnt(0)
	v_mfma_f32_32x32x16_bf16 v[96:111], v[248:251], v[124:127], v[96:111]
	s_setprio 0
	s_cmp_eq_u32 s56, 4
	s_cbranch_scc1 .Lw5_af2
	s_waitcnt vmcnt(4) lgkmcnt(0)
.Lw5_af2:
	s_waitcnt vmcnt(5) lgkmcnt(0)
	s_barrier
	s_add_i32 m0, s32, 0x20400
	s_add_u32 s80, s80, 0x20000
	s_addc_u32 s81, s81, 0
	global_load_lds_dwordx4 v128, s[80:81]
	s_add_i32 m0, m0, 0x2000
	s_nop 0
	global_load_lds_dwordx4 v129, s[80:81]
	s_add_i32 m0, s32, 0xd800
	s_nop 0
	global_load_lds_dwordx4 v130, s[80:81]
	s_add_i32 m0, m0, 0x2000
	s_cmp_eq_u32 s56, 4
	global_load_lds_dwordx4 v131, s[80:81]
	s_cbranch_scc0 .Lnod_af2
	s_mov_b32 m0, s28
	s_nop 0
	global_load_lds_dwordx4 v132, s[80:81]

.LAF0_top:
	s_cmp_ge_i32 s65, s69
	s_cbranch_scc1 .LA0_top
	v_add_u32_e32 v205, 0xa000, v165
	v_add_u32_e32 v206, 0x0, v192
	ds_read_b64_tr_b16 v[96:97], v205 offset:34816
	ds_read_b64_tr_b16 v[98:99], v205 offset:37376
	ds_read_b64_tr_b16 v[100:101], v205 offset:39936
	ds_read_b64_tr_b16 v[102:103], v205 offset:42496
	ds_read_b64_tr_b16 v[104:105], v205 offset:45056
	ds_read_b64_tr_b16 v[106:107], v205 offset:47616
	ds_read_b64_tr_b16 v[108:109], v205 offset:50176
	ds_read_b64_tr_b16 v[110:111], v205 offset:52736
	ds_read_b64_tr_b16 v[176:177], v205 offset:34880
	ds_read_b64_tr_b16 v[178:179], v205 offset:37440
	ds_read_b64_tr_b16 v[180:181], v205 offset:40000
	ds_read_b64_tr_b16 v[182:183], v205 offset:42560
	ds_read_b64_tr_b16 v[184:185], v205 offset:45120
	ds_read_b64_tr_b16 v[186:187], v205 offset:47680
	s_setprio 1
	s_waitcnt lgkmcnt(12)
	v_mfma_f32_32x32x16_bf16 v[32:47], v[96:99], v[80:83], v[32:47]
	ds_read_b64_tr_b16 v[96:97], v205 offset:50240
	ds_read_b64_tr_b16 v[98:99], v205 offset:52800
	s_waitcnt lgkmcnt(12)
	v_mfma_f32_32x32x16_bf16 v[32:47], v[100:103], v[84:87], v[32:47]
	ds_read_b64_tr_b16 v[100:101], v205 offset:34944
	ds_read_b64_tr_b16 v[102:103], v205 offset:37504
	s_waitcnt lgkmcnt(12)
	v_mfma_f32_32x32x16_bf16 v[32:47], v[104:107], v[88:91], v[32:47]
	ds_read_b64_tr_b16 v[104:105], v205 offset:40064
	ds_read_b64_tr_b16 v[106:107], v205 offset:42624
	s_waitcnt lgkmcnt(12)
	v_mfma_f32_32x32x16_bf16 v[32:47], v[108:111], v[92:95], v[32:47]
	ds_read_b64_tr_b16 v[108:109], v205 offset:45184
	ds_read_b64_tr_b16 v[110:111], v205 offset:47744
	s_waitcnt lgkmcnt(12)
	v_mfma_f32_32x32x16_bf16 v[16:31], v[176:179], v[80:83], v[16:31]
	ds_read_b64_tr_b16 v[176:177], v205 offset:50304
	ds_read_b64_tr_b16 v[178:179], v205 offset:52864
	s_waitcnt lgkmcnt(12)
	v_mfma_f32_32x32x16_bf16 v[16:31], v[180:183], v[84:87], v[16:31]
	ds_read_b64_tr_b16 v[180:181], v205 offset:35008
	ds_read_b64_tr_b16 v[182:183], v205 offset:37568
	s_waitcnt lgkmcnt(12)
	v_mfma_f32_32x32x16_bf16 v[16:31], v[184:187], v[88:91], v[16:31]
	ds_read_b64_tr_b16 v[184:185], v205 offset:40128
	ds_read_b64_tr_b16 v[186:187], v205 offset:42688
	s_waitcnt lgkmcnt(12)
	v_mfma_f32_32x32x16_bf16 v[16:31], v[96:99], v[92:95], v[16:31]
	ds_read_b64_tr_b16 v[96:97], v205 offset:45248
	ds_read_b64_tr_b16 v[98:99], v205 offset:47808
	s_waitcnt lgkmcnt(12)
	v_mfma_f32_32x32x16_bf16 v[0:15], v[100:103], v[80:83], v[0:15]
	ds_read_b64_tr_b16 v[100:101], v205 offset:50368
	ds_read_b64_tr_b16 v[102:103], v205 offset:52928
	s_waitcnt lgkmcnt(12)
	v_mfma_f32_32x32x16_bf16 v[0:15], v[104:107], v[84:87], v[0:15]
	ds_read_b128 v[210:213], v206 offset:8704
	ds_read_b128 v[104:107], v206 offset:8736
	s_waitcnt lgkmcnt(12)
	v_mfma_f32_32x32x16_bf16 v[0:15], v[108:111], v[88:91], v[0:15]
	ds_read_b128 v[108:111], v206 offset:8768
	ds_read_b128 v[188:191], v206
	s_waitcnt lgkmcnt(12)
	v_mfma_f32_32x32x16_bf16 v[0:15], v[176:179], v[92:95], v[0:15]
	ds_read_b128 v[176:179], v206 offset:8800
	ds_read_b128 v[224:227], v206 offset:32
	s_waitcnt lgkmcnt(12)
	v_mfma_f32_32x32x16_bf16 v[48:63], v[180:183], v[80:83], v[48:63]
	ds_read_b128 v[228:231], v206 offset:64
	ds_read_b128 v[248:251], v206 offset:96
	s_waitcnt lgkmcnt(12)
	v_mfma_f32_32x32x16_bf16 v[48:63], v[184:187], v[84:87], v[48:63]
	s_waitcnt lgkmcnt(10)
	v_mfma_f32_32x32x16_bf16 v[48:63], v[96:99], v[88:91], v[48:63]
	s_waitcnt lgkmcnt(8)
	v_mfma_f32_32x32x16_bf16 v[48:63], v[100:103], v[92:95], v[48:63]
	s_waitcnt lgkmcnt(7)
	v_mfma_f32_32x32x16_bf16 v[80:95], v[210:213], v[112:115], v[64:79]
	s_waitcnt lgkmcnt(6)
	v_mfma_f32_32x32x16_bf16 v[80:95], v[104:107], v[116:119], v[80:95]
	s_waitcnt lgkmcnt(5)
	v_mfma_f32_32x32x16_bf16 v[80:95], v[108:111], v[120:123], v[80:95]
	s_waitcnt lgkmcnt(3)
	v_mfma_f32_32x32x16_bf16 v[80:95], v[176:179], v[124:127], v[80:95]
	s_waitcnt lgkmcnt(4)
	v_mfma_f32_32x32x16_bf16 v[96:111], v[188:191], v[112:115], v[64:79]
	s_waitcnt lgkmcnt(2)
	v_mfma_f32_32x32x16_bf16 v[96:111], v[224:227], v[116:119], v[96:111]
	s_waitcnt lgkmcnt(1)
	v_mfma_f32_32x32x16_bf16 v[96:111], v[228:231], v[120:123], v[96:111]
	s_waitcnt lgkmcnt(0)
	v_mfma_f32_32x32x16_bf16 v[96:111], v[248:251], v[124:127], v[96:111]
	s_setprio 0
	s_cmp_eq_u32 s56, 4
	s_cbranch_scc1 .Lw5_af0
	s_waitcnt vmcnt(4) lgkmcnt(0)
.Lw5_af0:
	s_waitcnt vmcnt(5) lgkmcnt(0)
	s_barrier
	s_mov_b32 m0, s32
	s_add_u32 s80, s80, 0x20000
	s_addc_u32 s81, s81, 0
	global_load_lds_dwordx4 v128, s[80:81]
	s_add_i32 m0, m0, 0x2000
	s_nop 0
	global_load_lds_dwordx4 v129, s[80:81]
	s_add_i32 m0, s32, 0x12800
	s_nop 0
	global_load_lds_dwordx4 v130, s[80:81]
	s_add_i32 m0, m0, 0x2000
	s_cmp_eq_u32 s56, 4
	global_load_lds_dwordx4 v131, s[80:81]
	s_cbranch_scc0 .Lnod_af0
	s_mov_b32 m0, s29
	s_nop 0
	global_load_lds_dwordx4 v132, s[80:81]

.Latt_af0_exp:
	v_exp_f32_e32 v96, v96
	v_exp_f32_e32 v97, v97
	v_exp_f32_e32 v176, v80
	v_exp_f32_e32 v177, v81
	v_exp_f32_e32 v98, v98
	v_exp_f32_e32 v99, v99
	v_exp_f32_e32 v178, v82
	v_exp_f32_e32 v179, v83
	v_exp_f32_e32 v100, v100
	v_exp_f32_e32 v101, v101
	v_exp_f32_e32 v180, v84
	v_exp_f32_e32 v181, v85
	v_exp_f32_e32 v102, v102
	v_exp_f32_e32 v103, v103
	v_exp_f32_e32 v182, v86
	v_exp_f32_e32 v183, v87
	v_exp_f32_e32 v104, v104
	v_exp_f32_e32 v105, v105
	v_exp_f32_e32 v184, v88
	v_exp_f32_e32 v185, v89
	v_exp_f32_e32 v106, v106
	v_exp_f32_e32 v107, v107
	v_exp_f32_e32 v186, v90
	v_exp_f32_e32 v187, v91
	v_exp_f32_e32 v108, v108
	v_exp_f32_e32 v109, v109
	v_exp_f32_e32 v188, v92
	v_exp_f32_e32 v189, v93
	v_exp_f32_e32 v110, v110
	v_exp_f32_e32 v111, v111
	v_exp_f32_e32 v190, v94
	v_exp_f32_e32 v191, v95
	v_cvt_pk_bf16_f32 v80, v96, v97
	v_cvt_pk_bf16_f32 v81, v98, v99
	v_cvt_pk_bf16_f32 v82, v100, v101
	v_cvt_pk_bf16_f32 v83, v102, v103
	v_cvt_pk_bf16_f32 v84, v104, v105
	v_cvt_pk_bf16_f32 v85, v106, v107
	v_cvt_pk_bf16_f32 v86, v108, v109
	v_cvt_pk_bf16_f32 v87, v110, v111
	v_cvt_pk_bf16_f32 v88, v176, v177
	v_cvt_pk_bf16_f32 v89, v178, v179
	v_cvt_pk_bf16_f32 v90, v180, v181
	v_cvt_pk_bf16_f32 v91, v182, v183
	v_cvt_pk_bf16_f32 v92, v184, v185
	v_cvt_pk_bf16_f32 v93, v186, v187
	v_cvt_pk_bf16_f32 v94, v188, v189
	v_cvt_pk_bf16_f32 v95, v190, v191
	v_pk_add_f32 v[96:97], v[96:97], v[100:101]
	v_pk_add_f32 v[98:99], v[98:99], v[102:103]
	v_pk_add_f32 v[176:177], v[176:177], v[180:181]
	v_pk_add_f32 v[178:179], v[178:179], v[182:183]
	v_pk_add_f32 v[96:97], v[96:97], v[104:105]
	v_pk_add_f32 v[98:99], v[98:99], v[106:107]
	v_pk_add_f32 v[176:177], v[176:177], v[184:185]
	v_pk_add_f32 v[178:179], v[178:179], v[186:187]
	v_pk_add_f32 v[96:97], v[96:97], v[108:109]
	v_pk_add_f32 v[98:99], v[98:99], v[110:111]
	v_pk_add_f32 v[176:177], v[176:177], v[188:189]
	v_pk_add_f32 v[178:179], v[178:179], v[190:191]
	v_pk_add_f32 v[96:97], v[96:97], v[98:99]
	v_pk_add_f32 v[176:177], v[176:177], v[178:179]
	s_nop 0
	v_pk_add_f32 v[96:97], v[96:97], v[176:177]
	s_nop 0
	v_add_f32_e32 v96, v96, v97
	v_add_f32_e32 v172, v172, v96
	s_add_i32 s65, s65, 1
	s_add_i32 s33, s33, -1
	s_branch .LAF1_top

.LA0_end:
	s_add_i32 s65, s65, 1
	s_add_i32 s33, s33, -1
	s_cmp_gt_u32 s65, s66
	s_cbranch_scc1 .LA0_exit
	s_branch .LA1_top
.Lrs_bf1:
	v_max_f32_e32 v64, v176, v176
	v_max_f32_e32 v66, 0, v64
	v_exp_f32_e64 v176, -v66
	v_add_f32_e32 v173, v173, v66
	v_xor_b32_e32 v64, 0x80000000, v173
	v_pk_add_f32 v[96:97], v[96:97], v[66:67] op_sel_hi:[1,0] neg_lo:[0,1] neg_hi:[0,1]
	v_pk_add_f32 v[80:81], v[80:81], v[66:67] op_sel_hi:[1,0] neg_lo:[0,1] neg_hi:[0,1]
	v_pk_add_f32 v[98:99], v[98:99], v[66:67] op_sel_hi:[1,0] neg_lo:[0,1] neg_hi:[0,1]
	v_pk_add_f32 v[82:83], v[82:83], v[66:67] op_sel_hi:[1,0] neg_lo:[0,1] neg_hi:[0,1]
	v_pk_add_f32 v[100:101], v[100:101], v[66:67] op_sel_hi:[1,0] neg_lo:[0,1] neg_hi:[0,1]
	v_pk_add_f32 v[84:85], v[84:85], v[66:67] op_sel_hi:[1,0] neg_lo:[0,1] neg_hi:[0,1]
	v_pk_add_f32 v[102:103], v[102:103], v[66:67] op_sel_hi:[1,0] neg_lo:[0,1] neg_hi:[0,1]
	v_pk_add_f32 v[86:87], v[86:87], v[66:67] op_sel_hi:[1,0] neg_lo:[0,1] neg_hi:[0,1]
	v_pk_add_f32 v[104:105], v[104:105], v[66:67] op_sel_hi:[1,0] neg_lo:[0,1] neg_hi:[0,1]
	v_pk_add_f32 v[88:89], v[88:89], v[66:67] op_sel_hi:[1,0] neg_lo:[0,1] neg_hi:[0,1]
	v_pk_add_f32 v[106:107], v[106:107], v[66:67] op_sel_hi:[1,0] neg_lo:[0,1] neg_hi:[0,1]
	v_pk_add_f32 v[90:91], v[90:91], v[66:67] op_sel_hi:[1,0] neg_lo:[0,1] neg_hi:[0,1]
	v_pk_add_f32 v[108:109], v[108:109], v[66:67] op_sel_hi:[1,0] neg_lo:[0,1] neg_hi:[0,1]
	v_pk_add_f32 v[92:93], v[92:93], v[66:67] op_sel_hi:[1,0] neg_lo:[0,1] neg_hi:[0,1]
	v_pk_add_f32 v[110:111], v[110:111], v[66:67] op_sel_hi:[1,0] neg_lo:[0,1] neg_hi:[0,1]
	v_pk_add_f32 v[94:95], v[94:95], v[66:67] op_sel_hi:[1,0] neg_lo:[0,1] neg_hi:[0,1]
	v_mov_b32_e32 v65, v64
	v_mov_b32_e32 v66, v64
	v_mov_b32_e32 v67, v64
	v_mov_b32_e32 v68, v64
	v_mov_b32_e32 v69, v64
	v_mov_b32_e32 v70, v64
	v_mov_b32_e32 v71, v64
	v_mov_b32_e32 v72, v64
	v_mov_b32_e32 v73, v64
	v_mov_b32_e32 v74, v64
	v_mov_b32_e32 v75, v64
	v_mov_b32_e32 v76, v64
	v_mov_b32_e32 v77, v64
	v_mov_b32_e32 v78, v64
	v_mov_b32_e32 v79, v64
	v_pk_mul_f32 v[46:47], v[46:47], v[176:177] op_sel_hi:[1,0]
	v_pk_mul_f32 v[44:45], v[44:45], v[176:177] op_sel_hi:[1,0]
	v_pk_mul_f32 v[42:43], v[42:43], v[176:177] op_sel_hi:[1,0]
	v_pk_mul_f32 v[40:41], v[40:41], v[176:177] op_sel_hi:[1,0]
	v_pk_mul_f32 v[38:39], v[38:39], v[176:177] op_sel_hi:[1,0]
	v_pk_mul_f32 v[36:37], v[36:37], v[176:177] op_sel_hi:[1,0]
	v_pk_mul_f32 v[34:35], v[34:35], v[176:177] op_sel_hi:[1,0]
	v_pk_mul_f32 v[32:33], v[32:33], v[176:177] op_sel_hi:[1,0]
	v_pk_mul_f32 v[30:31], v[30:31], v[176:177] op_sel_hi:[1,0]
	v_pk_mul_f32 v[28:29], v[28:29], v[176:177] op_sel_hi:[1,0]
	v_pk_mul_f32 v[26:27], v[26:27], v[176:177] op_sel_hi:[1,0]
	v_pk_mul_f32 v[24:25], v[24:25], v[176:177] op_sel_hi:[1,0]
	v_pk_mul_f32 v[22:23], v[22:23], v[176:177] op_sel_hi:[1,0]
	v_pk_mul_f32 v[20:21], v[20:21], v[176:177] op_sel_hi:[1,0]
	v_pk_mul_f32 v[18:19], v[18:19], v[176:177] op_sel_hi:[1,0]
	v_pk_mul_f32 v[16:17], v[16:17], v[176:177] op_sel_hi:[1,0]
	v_pk_mul_f32 v[14:15], v[14:15], v[176:177] op_sel_hi:[1,0]
	v_pk_mul_f32 v[12:13], v[12:13], v[176:177] op_sel_hi:[1,0]
	v_pk_mul_f32 v[10:11], v[10:11], v[176:177] op_sel_hi:[1,0]
	v_pk_mul_f32 v[8:9], v[8:9], v[176:177] op_sel_hi:[1,0]
	v_pk_mul_f32 v[6:7], v[6:7], v[176:177] op_sel_hi:[1,0]
	v_pk_mul_f32 v[4:5], v[4:5], v[176:177] op_sel_hi:[1,0]
	v_pk_mul_f32 v[2:3], v[2:3], v[176:177] op_sel_hi:[1,0]
	v_pk_mul_f32 v[0:1], v[0:1], v[176:177] op_sel_hi:[1,0]
	v_pk_mul_f32 v[62:63], v[62:63], v[176:177] op_sel_hi:[1,0]
	v_pk_mul_f32 v[60:61], v[60:61], v[176:177] op_sel_hi:[1,0]
	v_pk_mul_f32 v[58:59], v[58:59], v[176:177] op_sel_hi:[1,0]
	v_pk_mul_f32 v[56:57], v[56:57], v[176:177] op_sel_hi:[1,0]
	v_pk_mul_f32 v[54:55], v[54:55], v[176:177] op_sel_hi:[1,0]
	v_pk_mul_f32 v[52:53], v[52:53], v[176:177] op_sel_hi:[1,0]
	v_pk_mul_f32 v[50:51], v[50:51], v[176:177] op_sel_hi:[1,0]
	v_pk_mul_f32 v[48:49], v[48:49], v[176:177] op_sel_hi:[1,0]
	v_mul_f32_e32 v172, v172, v176
	s_branch .Latt_bf1_exp
.Lrs_bf2:
	v_max_f32_e32 v64, v176, v176
	v_max_f32_e32 v66, 0, v64
	v_exp_f32_e64 v176, -v66
	v_add_f32_e32 v173, v173, v66
	v_xor_b32_e32 v64, 0x80000000, v173
	v_pk_add_f32 v[96:97], v[96:97], v[66:67] op_sel_hi:[1,0] neg_lo:[0,1] neg_hi:[0,1]
	v_pk_add_f32 v[80:81], v[80:81], v[66:67] op_sel_hi:[1,0] neg_lo:[0,1] neg_hi:[0,1]
	v_pk_add_f32 v[98:99], v[98:99], v[66:67] op_sel_hi:[1,0] neg_lo:[0,1] neg_hi:[0,1]
	v_pk_add_f32 v[82:83], v[82:83], v[66:67] op_sel_hi:[1,0] neg_lo:[0,1] neg_hi:[0,1]
	v_pk_add_f32 v[100:101], v[100:101], v[66:67] op_sel_hi:[1,0] neg_lo:[0,1] neg_hi:[0,1]
	v_pk_add_f32 v[84:85], v[84:85], v[66:67] op_sel_hi:[1,0] neg_lo:[0,1] neg_hi:[0,1]
	v_pk_add_f32 v[102:103], v[102:103], v[66:67] op_sel_hi:[1,0] neg_lo:[0,1] neg_hi:[0,1]
	v_pk_add_f32 v[86:87], v[86:87], v[66:67] op_sel_hi:[1,0] neg_lo:[0,1] neg_hi:[0,1]
	v_pk_add_f32 v[104:105], v[104:105], v[66:67] op_sel_hi:[1,0] neg_lo:[0,1] neg_hi:[0,1]
	v_pk_add_f32 v[88:89], v[88:89], v[66:67] op_sel_hi:[1,0] neg_lo:[0,1] neg_hi:[0,1]
	v_pk_add_f32 v[106:107], v[106:107], v[66:67] op_sel_hi:[1,0] neg_lo:[0,1] neg_hi:[0,1]
	v_pk_add_f32 v[90:91], v[90:91], v[66:67] op_sel_hi:[1,0] neg_lo:[0,1] neg_hi:[0,1]
	v_pk_add_f32 v[108:109], v[108:109], v[66:67] op_sel_hi:[1,0] neg_lo:[0,1] neg_hi:[0,1]
	v_pk_add_f32 v[92:93], v[92:93], v[66:67] op_sel_hi:[1,0] neg_lo:[0,1] neg_hi:[0,1]
	v_pk_add_f32 v[110:111], v[110:111], v[66:67] op_sel_hi:[1,0] neg_lo:[0,1] neg_hi:[0,1]
	v_pk_add_f32 v[94:95], v[94:95], v[66:67] op_sel_hi:[1,0] neg_lo:[0,1] neg_hi:[0,1]
	v_mov_b32_e32 v65, v64
	v_mov_b32_e32 v66, v64
	v_mov_b32_e32 v67, v64
	v_mov_b32_e32 v68, v64
	v_mov_b32_e32 v69, v64
	v_mov_b32_e32 v70, v64
	v_mov_b32_e32 v71, v64
	v_mov_b32_e32 v72, v64
	v_mov_b32_e32 v73, v64
	v_mov_b32_e32 v74, v64
	v_mov_b32_e32 v75, v64
	v_mov_b32_e32 v76, v64
	v_mov_b32_e32 v77, v64
	v_mov_b32_e32 v78, v64
	v_mov_b32_e32 v79, v64
	v_pk_mul_f32 v[46:47], v[46:47], v[176:177] op_sel_hi:[1,0]
	v_pk_mul_f32 v[44:45], v[44:45], v[176:177] op_sel_hi:[1,0]
	v_pk_mul_f32 v[42:43], v[42:43], v[176:177] op_sel_hi:[1,0]
	v_pk_mul_f32 v[40:41], v[40:41], v[176:177] op_sel_hi:[1,0]
	v_pk_mul_f32 v[38:39], v[38:39], v[176:177] op_sel_hi:[1,0]
	v_pk_mul_f32 v[36:37], v[36:37], v[176:177] op_sel_hi:[1,0]
	v_pk_mul_f32 v[34:35], v[34:35], v[176:177] op_sel_hi:[1,0]
	v_pk_mul_f32 v[32:33], v[32:33], v[176:177] op_sel_hi:[1,0]
	v_pk_mul_f32 v[30:31], v[30:31], v[176:177] op_sel_hi:[1,0]
	v_pk_mul_f32 v[28:29], v[28:29], v[176:177] op_sel_hi:[1,0]
	v_pk_mul_f32 v[26:27], v[26:27], v[176:177] op_sel_hi:[1,0]
	v_pk_mul_f32 v[24:25], v[24:25], v[176:177] op_sel_hi:[1,0]
	v_pk_mul_f32 v[22:23], v[22:23], v[176:177] op_sel_hi:[1,0]
	v_pk_mul_f32 v[20:21], v[20:21], v[176:177] op_sel_hi:[1,0]
	v_pk_mul_f32 v[18:19], v[18:19], v[176:177] op_sel_hi:[1,0]
	v_pk_mul_f32 v[16:17], v[16:17], v[176:177] op_sel_hi:[1,0]
	v_pk_mul_f32 v[14:15], v[14:15], v[176:177] op_sel_hi:[1,0]
	v_pk_mul_f32 v[12:13], v[12:13], v[176:177] op_sel_hi:[1,0]
	v_pk_mul_f32 v[10:11], v[10:11], v[176:177] op_sel_hi:[1,0]
	v_pk_mul_f32 v[8:9], v[8:9], v[176:177] op_sel_hi:[1,0]
	v_pk_mul_f32 v[6:7], v[6:7], v[176:177] op_sel_hi:[1,0]
	v_pk_mul_f32 v[4:5], v[4:5], v[176:177] op_sel_hi:[1,0]
	v_pk_mul_f32 v[2:3], v[2:3], v[176:177] op_sel_hi:[1,0]
	v_pk_mul_f32 v[0:1], v[0:1], v[176:177] op_sel_hi:[1,0]
	v_pk_mul_f32 v[62:63], v[62:63], v[176:177] op_sel_hi:[1,0]
	v_pk_mul_f32 v[60:61], v[60:61], v[176:177] op_sel_hi:[1,0]
	v_pk_mul_f32 v[58:59], v[58:59], v[176:177] op_sel_hi:[1,0]
	v_pk_mul_f32 v[56:57], v[56:57], v[176:177] op_sel_hi:[1,0]
	v_pk_mul_f32 v[54:55], v[54:55], v[176:177] op_sel_hi:[1,0]
	v_pk_mul_f32 v[52:53], v[52:53], v[176:177] op_sel_hi:[1,0]
	v_pk_mul_f32 v[50:51], v[50:51], v[176:177] op_sel_hi:[1,0]
	v_pk_mul_f32 v[48:49], v[48:49], v[176:177] op_sel_hi:[1,0]
	v_mul_f32_e32 v172, v172, v176
	s_branch .Latt_bf2_exp
.Lrs_bf0:
	v_max_f32_e32 v64, v176, v176
	v_max_f32_e32 v66, 0, v64
	v_exp_f32_e64 v176, -v66
	v_add_f32_e32 v173, v173, v66
	v_xor_b32_e32 v64, 0x80000000, v173
	v_pk_add_f32 v[96:97], v[96:97], v[66:67] op_sel_hi:[1,0] neg_lo:[0,1] neg_hi:[0,1]
	v_pk_add_f32 v[80:81], v[80:81], v[66:67] op_sel_hi:[1,0] neg_lo:[0,1] neg_hi:[0,1]
	v_pk_add_f32 v[98:99], v[98:99], v[66:67] op_sel_hi:[1,0] neg_lo:[0,1] neg_hi:[0,1]
	v_pk_add_f32 v[82:83], v[82:83], v[66:67] op_sel_hi:[1,0] neg_lo:[0,1] neg_hi:[0,1]
	v_pk_add_f32 v[100:101], v[100:101], v[66:67] op_sel_hi:[1,0] neg_lo:[0,1] neg_hi:[0,1]
	v_pk_add_f32 v[84:85], v[84:85], v[66:67] op_sel_hi:[1,0] neg_lo:[0,1] neg_hi:[0,1]
	v_pk_add_f32 v[102:103], v[102:103], v[66:67] op_sel_hi:[1,0] neg_lo:[0,1] neg_hi:[0,1]
	v_pk_add_f32 v[86:87], v[86:87], v[66:67] op_sel_hi:[1,0] neg_lo:[0,1] neg_hi:[0,1]
	v_pk_add_f32 v[104:105], v[104:105], v[66:67] op_sel_hi:[1,0] neg_lo:[0,1] neg_hi:[0,1]
	v_pk_add_f32 v[88:89], v[88:89], v[66:67] op_sel_hi:[1,0] neg_lo:[0,1] neg_hi:[0,1]
	v_pk_add_f32 v[106:107], v[106:107], v[66:67] op_sel_hi:[1,0] neg_lo:[0,1] neg_hi:[0,1]
	v_pk_add_f32 v[90:91], v[90:91], v[66:67] op_sel_hi:[1,0] neg_lo:[0,1] neg_hi:[0,1]
	v_pk_add_f32 v[108:109], v[108:109], v[66:67] op_sel_hi:[1,0] neg_lo:[0,1] neg_hi:[0,1]
	v_pk_add_f32 v[92:93], v[92:93], v[66:67] op_sel_hi:[1,0] neg_lo:[0,1] neg_hi:[0,1]
	v_pk_add_f32 v[110:111], v[110:111], v[66:67] op_sel_hi:[1,0] neg_lo:[0,1] neg_hi:[0,1]
	v_pk_add_f32 v[94:95], v[94:95], v[66:67] op_sel_hi:[1,0] neg_lo:[0,1] neg_hi:[0,1]
	v_mov_b32_e32 v65, v64
	v_mov_b32_e32 v66, v64
	v_mov_b32_e32 v67, v64
	v_mov_b32_e32 v68, v64
	v_mov_b32_e32 v69, v64
	v_mov_b32_e32 v70, v64
	v_mov_b32_e32 v71, v64
	v_mov_b32_e32 v72, v64
	v_mov_b32_e32 v73, v64
	v_mov_b32_e32 v74, v64
	v_mov_b32_e32 v75, v64
	v_mov_b32_e32 v76, v64
	v_mov_b32_e32 v77, v64
	v_mov_b32_e32 v78, v64
	v_mov_b32_e32 v79, v64
	v_pk_mul_f32 v[46:47], v[46:47], v[176:177] op_sel_hi:[1,0]
	v_pk_mul_f32 v[44:45], v[44:45], v[176:177] op_sel_hi:[1,0]
	v_pk_mul_f32 v[42:43], v[42:43], v[176:177] op_sel_hi:[1,0]
	v_pk_mul_f32 v[40:41], v[40:41], v[176:177] op_sel_hi:[1,0]
	v_pk_mul_f32 v[38:39], v[38:39], v[176:177] op_sel_hi:[1,0]
	v_pk_mul_f32 v[36:37], v[36:37], v[176:177] op_sel_hi:[1,0]
	v_pk_mul_f32 v[34:35], v[34:35], v[176:177] op_sel_hi:[1,0]
	v_pk_mul_f32 v[32:33], v[32:33], v[176:177] op_sel_hi:[1,0]
	v_pk_mul_f32 v[30:31], v[30:31], v[176:177] op_sel_hi:[1,0]
	v_pk_mul_f32 v[28:29], v[28:29], v[176:177] op_sel_hi:[1,0]
	v_pk_mul_f32 v[26:27], v[26:27], v[176:177] op_sel_hi:[1,0]
	v_pk_mul_f32 v[24:25], v[24:25], v[176:177] op_sel_hi:[1,0]
	v_pk_mul_f32 v[22:23], v[22:23], v[176:177] op_sel_hi:[1,0]
	v_pk_mul_f32 v[20:21], v[20:21], v[176:177] op_sel_hi:[1,0]
	v_pk_mul_f32 v[18:19], v[18:19], v[176:177] op_sel_hi:[1,0]
	v_pk_mul_f32 v[16:17], v[16:17], v[176:177] op_sel_hi:[1,0]
	v_pk_mul_f32 v[14:15], v[14:15], v[176:177] op_sel_hi:[1,0]
	v_pk_mul_f32 v[12:13], v[12:13], v[176:177] op_sel_hi:[1,0]
	v_pk_mul_f32 v[10:11], v[10:11], v[176:177] op_sel_hi:[1,0]
	v_pk_mul_f32 v[8:9], v[8:9], v[176:177] op_sel_hi:[1,0]
	v_pk_mul_f32 v[6:7], v[6:7], v[176:177] op_sel_hi:[1,0]
	v_pk_mul_f32 v[4:5], v[4:5], v[176:177] op_sel_hi:[1,0]
	v_pk_mul_f32 v[2:3], v[2:3], v[176:177] op_sel_hi:[1,0]
	v_pk_mul_f32 v[0:1], v[0:1], v[176:177] op_sel_hi:[1,0]
	v_pk_mul_f32 v[62:63], v[62:63], v[176:177] op_sel_hi:[1,0]
	v_pk_mul_f32 v[60:61], v[60:61], v[176:177] op_sel_hi:[1,0]
	v_pk_mul_f32 v[58:59], v[58:59], v[176:177] op_sel_hi:[1,0]
	v_pk_mul_f32 v[56:57], v[56:57], v[176:177] op_sel_hi:[1,0]
	v_pk_mul_f32 v[54:55], v[54:55], v[176:177] op_sel_hi:[1,0]
	v_pk_mul_f32 v[52:53], v[52:53], v[176:177] op_sel_hi:[1,0]
	v_pk_mul_f32 v[50:51], v[50:51], v[176:177] op_sel_hi:[1,0]
	v_pk_mul_f32 v[48:49], v[48:49], v[176:177] op_sel_hi:[1,0]
	v_mul_f32_e32 v172, v172, v176
	s_branch .Latt_bf0_exp
.Ltl_b1:
	s_cmp_ge_u32 s65, s66
	s_cbranch_scc1 .Ltl2_b1
	s_add_u32 s80, s80, 0x20000
	s_addc_u32 s81, s81, 0
	s_add_i32 m0, s32, 0x12800
	s_nop 0
	global_load_lds_dwordx4 v130, s[80:81]
	s_add_i32 m0, m0, 0x2000
	s_cmp_eq_u32 s56, 0
	global_load_lds_dwordx4 v131, s[80:81]
	s_cbranch_scc1 .Ltl2_b1
	s_mov_b32 m0, s5
	s_nop 0
	global_load_lds_dwordx4 v132, s[80:81]

.LB0_exit:
	s_mov_b32 s69, 0
	s_branch .LBB0_243
.Lrs_af1:
	v_max_f32_e32 v64, v176, v176
	v_max_f32_e32 v66, 0, v64
	v_exp_f32_e64 v176, -v66
	v_add_f32_e32 v173, v173, v66
	v_xor_b32_e32 v64, 0x80000000, v173
	v_pk_add_f32 v[96:97], v[96:97], v[66:67] op_sel_hi:[1,0] neg_lo:[0,1] neg_hi:[0,1]
	v_pk_add_f32 v[80:81], v[80:81], v[66:67] op_sel_hi:[1,0] neg_lo:[0,1] neg_hi:[0,1]
	v_pk_add_f32 v[98:99], v[98:99], v[66:67] op_sel_hi:[1,0] neg_lo:[0,1] neg_hi:[0,1]
	v_pk_add_f32 v[82:83], v[82:83], v[66:67] op_sel_hi:[1,0] neg_lo:[0,1] neg_hi:[0,1]
	v_pk_add_f32 v[100:101], v[100:101], v[66:67] op_sel_hi:[1,0] neg_lo:[0,1] neg_hi:[0,1]
	v_pk_add_f32 v[84:85], v[84:85], v[66:67] op_sel_hi:[1,0] neg_lo:[0,1] neg_hi:[0,1]
	v_pk_add_f32 v[102:103], v[102:103], v[66:67] op_sel_hi:[1,0] neg_lo:[0,1] neg_hi:[0,1]
	v_pk_add_f32 v[86:87], v[86:87], v[66:67] op_sel_hi:[1,0] neg_lo:[0,1] neg_hi:[0,1]
	v_pk_add_f32 v[104:105], v[104:105], v[66:67] op_sel_hi:[1,0] neg_lo:[0,1] neg_hi:[0,1]
	v_pk_add_f32 v[88:89], v[88:89], v[66:67] op_sel_hi:[1,0] neg_lo:[0,1] neg_hi:[0,1]
	v_pk_add_f32 v[106:107], v[106:107], v[66:67] op_sel_hi:[1,0] neg_lo:[0,1] neg_hi:[0,1]
	v_pk_add_f32 v[90:91], v[90:91], v[66:67] op_sel_hi:[1,0] neg_lo:[0,1] neg_hi:[0,1]
	v_pk_add_f32 v[108:109], v[108:109], v[66:67] op_sel_hi:[1,0] neg_lo:[0,1] neg_hi:[0,1]
	v_pk_add_f32 v[92:93], v[92:93], v[66:67] op_sel_hi:[1,0] neg_lo:[0,1] neg_hi:[0,1]
	v_pk_add_f32 v[110:111], v[110:111], v[66:67] op_sel_hi:[1,0] neg_lo:[0,1] neg_hi:[0,1]
	v_pk_add_f32 v[94:95], v[94:95], v[66:67] op_sel_hi:[1,0] neg_lo:[0,1] neg_hi:[0,1]
	v_mov_b32_e32 v65, v64
	v_mov_b32_e32 v66, v64
	v_mov_b32_e32 v67, v64
	v_mov_b32_e32 v68, v64
	v_mov_b32_e32 v69, v64
	v_mov_b32_e32 v70, v64
	v_mov_b32_e32 v71, v64
	v_mov_b32_e32 v72, v64
	v_mov_b32_e32 v73, v64
	v_mov_b32_e32 v74, v64
	v_mov_b32_e32 v75, v64
	v_mov_b32_e32 v76, v64
	v_mov_b32_e32 v77, v64
	v_mov_b32_e32 v78, v64
	v_mov_b32_e32 v79, v64
	v_pk_mul_f32 v[46:47], v[46:47], v[176:177] op_sel_hi:[1,0]
	v_pk_mul_f32 v[44:45], v[44:45], v[176:177] op_sel_hi:[1,0]
	v_pk_mul_f32 v[42:43], v[42:43], v[176:177] op_sel_hi:[1,0]
	v_pk_mul_f32 v[40:41], v[40:41], v[176:177] op_sel_hi:[1,0]
	v_pk_mul_f32 v[38:39], v[38:39], v[176:177] op_sel_hi:[1,0]
	v_pk_mul_f32 v[36:37], v[36:37], v[176:177] op_sel_hi:[1,0]
	v_pk_mul_f32 v[34:35], v[34:35], v[176:177] op_sel_hi:[1,0]
	v_pk_mul_f32 v[32:33], v[32:33], v[176:177] op_sel_hi:[1,0]
	v_pk_mul_f32 v[30:31], v[30:31], v[176:177] op_sel_hi:[1,0]
	v_pk_mul_f32 v[28:29], v[28:29], v[176:177] op_sel_hi:[1,0]
	v_pk_mul_f32 v[26:27], v[26:27], v[176:177] op_sel_hi:[1,0]
	v_pk_mul_f32 v[24:25], v[24:25], v[176:177] op_sel_hi:[1,0]
	v_pk_mul_f32 v[22:23], v[22:23], v[176:177] op_sel_hi:[1,0]
	v_pk_mul_f32 v[20:21], v[20:21], v[176:177] op_sel_hi:[1,0]
	v_pk_mul_f32 v[18:19], v[18:19], v[176:177] op_sel_hi:[1,0]
	v_pk_mul_f32 v[16:17], v[16:17], v[176:177] op_sel_hi:[1,0]
	v_pk_mul_f32 v[14:15], v[14:15], v[176:177] op_sel_hi:[1,0]
	v_pk_mul_f32 v[12:13], v[12:13], v[176:177] op_sel_hi:[1,0]
	v_pk_mul_f32 v[10:11], v[10:11], v[176:177] op_sel_hi:[1,0]
	v_pk_mul_f32 v[8:9], v[8:9], v[176:177] op_sel_hi:[1,0]
	v_pk_mul_f32 v[6:7], v[6:7], v[176:177] op_sel_hi:[1,0]
	v_pk_mul_f32 v[4:5], v[4:5], v[176:177] op_sel_hi:[1,0]
	v_pk_mul_f32 v[2:3], v[2:3], v[176:177] op_sel_hi:[1,0]
	v_pk_mul_f32 v[0:1], v[0:1], v[176:177] op_sel_hi:[1,0]
	v_pk_mul_f32 v[62:63], v[62:63], v[176:177] op_sel_hi:[1,0]
	v_pk_mul_f32 v[60:61], v[60:61], v[176:177] op_sel_hi:[1,0]
	v_pk_mul_f32 v[58:59], v[58:59], v[176:177] op_sel_hi:[1,0]
	v_pk_mul_f32 v[56:57], v[56:57], v[176:177] op_sel_hi:[1,0]
	v_pk_mul_f32 v[54:55], v[54:55], v[176:177] op_sel_hi:[1,0]
	v_pk_mul_f32 v[52:53], v[52:53], v[176:177] op_sel_hi:[1,0]
	v_pk_mul_f32 v[50:51], v[50:51], v[176:177] op_sel_hi:[1,0]
	v_pk_mul_f32 v[48:49], v[48:49], v[176:177] op_sel_hi:[1,0]
	v_mul_f32_e32 v172, v172, v176
	s_branch .Latt_af1_exp
.Lrs_af2:
	v_max_f32_e32 v64, v176, v176
	v_max_f32_e32 v66, 0, v64
	v_exp_f32_e64 v176, -v66
	v_add_f32_e32 v173, v173, v66
	v_xor_b32_e32 v64, 0x80000000, v173
	v_pk_add_f32 v[96:97], v[96:97], v[66:67] op_sel_hi:[1,0] neg_lo:[0,1] neg_hi:[0,1]
	v_pk_add_f32 v[80:81], v[80:81], v[66:67] op_sel_hi:[1,0] neg_lo:[0,1] neg_hi:[0,1]
	v_pk_add_f32 v[98:99], v[98:99], v[66:67] op_sel_hi:[1,0] neg_lo:[0,1] neg_hi:[0,1]
	v_pk_add_f32 v[82:83], v[82:83], v[66:67] op_sel_hi:[1,0] neg_lo:[0,1] neg_hi:[0,1]
	v_pk_add_f32 v[100:101], v[100:101], v[66:67] op_sel_hi:[1,0] neg_lo:[0,1] neg_hi:[0,1]
	v_pk_add_f32 v[84:85], v[84:85], v[66:67] op_sel_hi:[1,0] neg_lo:[0,1] neg_hi:[0,1]
	v_pk_add_f32 v[102:103], v[102:103], v[66:67] op_sel_hi:[1,0] neg_lo:[0,1] neg_hi:[0,1]
	v_pk_add_f32 v[86:87], v[86:87], v[66:67] op_sel_hi:[1,0] neg_lo:[0,1] neg_hi:[0,1]
	v_pk_add_f32 v[104:105], v[104:105], v[66:67] op_sel_hi:[1,0] neg_lo:[0,1] neg_hi:[0,1]
	v_pk_add_f32 v[88:89], v[88:89], v[66:67] op_sel_hi:[1,0] neg_lo:[0,1] neg_hi:[0,1]
	v_pk_add_f32 v[106:107], v[106:107], v[66:67] op_sel_hi:[1,0] neg_lo:[0,1] neg_hi:[0,1]
	v_pk_add_f32 v[90:91], v[90:91], v[66:67] op_sel_hi:[1,0] neg_lo:[0,1] neg_hi:[0,1]
	v_pk_add_f32 v[108:109], v[108:109], v[66:67] op_sel_hi:[1,0] neg_lo:[0,1] neg_hi:[0,1]
	v_pk_add_f32 v[92:93], v[92:93], v[66:67] op_sel_hi:[1,0] neg_lo:[0,1] neg_hi:[0,1]
	v_pk_add_f32 v[110:111], v[110:111], v[66:67] op_sel_hi:[1,0] neg_lo:[0,1] neg_hi:[0,1]
	v_pk_add_f32 v[94:95], v[94:95], v[66:67] op_sel_hi:[1,0] neg_lo:[0,1] neg_hi:[0,1]
	v_mov_b32_e32 v65, v64
	v_mov_b32_e32 v66, v64
	v_mov_b32_e32 v67, v64
	v_mov_b32_e32 v68, v64
	v_mov_b32_e32 v69, v64
	v_mov_b32_e32 v70, v64
	v_mov_b32_e32 v71, v64
	v_mov_b32_e32 v72, v64
	v_mov_b32_e32 v73, v64
	v_mov_b32_e32 v74, v64
	v_mov_b32_e32 v75, v64
	v_mov_b32_e32 v76, v64
	v_mov_b32_e32 v77, v64
	v_mov_b32_e32 v78, v64
	v_mov_b32_e32 v79, v64
	v_pk_mul_f32 v[46:47], v[46:47], v[176:177] op_sel_hi:[1,0]
	v_pk_mul_f32 v[44:45], v[44:45], v[176:177] op_sel_hi:[1,0]
	v_pk_mul_f32 v[42:43], v[42:43], v[176:177] op_sel_hi:[1,0]
	v_pk_mul_f32 v[40:41], v[40:41], v[176:177] op_sel_hi:[1,0]
	v_pk_mul_f32 v[38:39], v[38:39], v[176:177] op_sel_hi:[1,0]
	v_pk_mul_f32 v[36:37], v[36:37], v[176:177] op_sel_hi:[1,0]
	v_pk_mul_f32 v[34:35], v[34:35], v[176:177] op_sel_hi:[1,0]
	v_pk_mul_f32 v[32:33], v[32:33], v[176:177] op_sel_hi:[1,0]
	v_pk_mul_f32 v[30:31], v[30:31], v[176:177] op_sel_hi:[1,0]
	v_pk_mul_f32 v[28:29], v[28:29], v[176:177] op_sel_hi:[1,0]
	v_pk_mul_f32 v[26:27], v[26:27], v[176:177] op_sel_hi:[1,0]
	v_pk_mul_f32 v[24:25], v[24:25], v[176:177] op_sel_hi:[1,0]
	v_pk_mul_f32 v[22:23], v[22:23], v[176:177] op_sel_hi:[1,0]
	v_pk_mul_f32 v[20:21], v[20:21], v[176:177] op_sel_hi:[1,0]
	v_pk_mul_f32 v[18:19], v[18:19], v[176:177] op_sel_hi:[1,0]
	v_pk_mul_f32 v[16:17], v[16:17], v[176:177] op_sel_hi:[1,0]
	v_pk_mul_f32 v[14:15], v[14:15], v[176:177] op_sel_hi:[1,0]
	v_pk_mul_f32 v[12:13], v[12:13], v[176:177] op_sel_hi:[1,0]
	v_pk_mul_f32 v[10:11], v[10:11], v[176:177] op_sel_hi:[1,0]
	v_pk_mul_f32 v[8:9], v[8:9], v[176:177] op_sel_hi:[1,0]
	v_pk_mul_f32 v[6:7], v[6:7], v[176:177] op_sel_hi:[1,0]
	v_pk_mul_f32 v[4:5], v[4:5], v[176:177] op_sel_hi:[1,0]
	v_pk_mul_f32 v[2:3], v[2:3], v[176:177] op_sel_hi:[1,0]
	v_pk_mul_f32 v[0:1], v[0:1], v[176:177] op_sel_hi:[1,0]
	v_pk_mul_f32 v[62:63], v[62:63], v[176:177] op_sel_hi:[1,0]
	v_pk_mul_f32 v[60:61], v[60:61], v[176:177] op_sel_hi:[1,0]
	v_pk_mul_f32 v[58:59], v[58:59], v[176:177] op_sel_hi:[1,0]
	v_pk_mul_f32 v[56:57], v[56:57], v[176:177] op_sel_hi:[1,0]
	v_pk_mul_f32 v[54:55], v[54:55], v[176:177] op_sel_hi:[1,0]
	v_pk_mul_f32 v[52:53], v[52:53], v[176:177] op_sel_hi:[1,0]
	v_pk_mul_f32 v[50:51], v[50:51], v[176:177] op_sel_hi:[1,0]
	v_pk_mul_f32 v[48:49], v[48:49], v[176:177] op_sel_hi:[1,0]
	v_mul_f32_e32 v172, v172, v176
	s_branch .Latt_af2_exp
.Lrs_af0:
	v_max_f32_e32 v64, v176, v176
	v_max_f32_e32 v66, 0, v64
	v_exp_f32_e64 v176, -v66
	v_add_f32_e32 v173, v173, v66
	v_xor_b32_e32 v64, 0x80000000, v173
	v_pk_add_f32 v[96:97], v[96:97], v[66:67] op_sel_hi:[1,0] neg_lo:[0,1] neg_hi:[0,1]
	v_pk_add_f32 v[80:81], v[80:81], v[66:67] op_sel_hi:[1,0] neg_lo:[0,1] neg_hi:[0,1]
	v_pk_add_f32 v[98:99], v[98:99], v[66:67] op_sel_hi:[1,0] neg_lo:[0,1] neg_hi:[0,1]
	v_pk_add_f32 v[82:83], v[82:83], v[66:67] op_sel_hi:[1,0] neg_lo:[0,1] neg_hi:[0,1]
	v_pk_add_f32 v[100:101], v[100:101], v[66:67] op_sel_hi:[1,0] neg_lo:[0,1] neg_hi:[0,1]
	v_pk_add_f32 v[84:85], v[84:85], v[66:67] op_sel_hi:[1,0] neg_lo:[0,1] neg_hi:[0,1]
	v_pk_add_f32 v[102:103], v[102:103], v[66:67] op_sel_hi:[1,0] neg_lo:[0,1] neg_hi:[0,1]
	v_pk_add_f32 v[86:87], v[86:87], v[66:67] op_sel_hi:[1,0] neg_lo:[0,1] neg_hi:[0,1]
	v_pk_add_f32 v[104:105], v[104:105], v[66:67] op_sel_hi:[1,0] neg_lo:[0,1] neg_hi:[0,1]
	v_pk_add_f32 v[88:89], v[88:89], v[66:67] op_sel_hi:[1,0] neg_lo:[0,1] neg_hi:[0,1]
	v_pk_add_f32 v[106:107], v[106:107], v[66:67] op_sel_hi:[1,0] neg_lo:[0,1] neg_hi:[0,1]
	v_pk_add_f32 v[90:91], v[90:91], v[66:67] op_sel_hi:[1,0] neg_lo:[0,1] neg_hi:[0,1]
	v_pk_add_f32 v[108:109], v[108:109], v[66:67] op_sel_hi:[1,0] neg_lo:[0,1] neg_hi:[0,1]
	v_pk_add_f32 v[92:93], v[92:93], v[66:67] op_sel_hi:[1,0] neg_lo:[0,1] neg_hi:[0,1]
	v_pk_add_f32 v[110:111], v[110:111], v[66:67] op_sel_hi:[1,0] neg_lo:[0,1] neg_hi:[0,1]
	v_pk_add_f32 v[94:95], v[94:95], v[66:67] op_sel_hi:[1,0] neg_lo:[0,1] neg_hi:[0,1]
	v_mov_b32_e32 v65, v64
	v_mov_b32_e32 v66, v64
	v_mov_b32_e32 v67, v64
	v_mov_b32_e32 v68, v64
	v_mov_b32_e32 v69, v64
	v_mov_b32_e32 v70, v64
	v_mov_b32_e32 v71, v64
	v_mov_b32_e32 v72, v64
	v_mov_b32_e32 v73, v64
	v_mov_b32_e32 v74, v64
	v_mov_b32_e32 v75, v64
	v_mov_b32_e32 v76, v64
	v_mov_b32_e32 v77, v64
	v_mov_b32_e32 v78, v64
	v_mov_b32_e32 v79, v64
	v_pk_mul_f32 v[46:47], v[46:47], v[176:177] op_sel_hi:[1,0]
	v_pk_mul_f32 v[44:45], v[44:45], v[176:177] op_sel_hi:[1,0]
	v_pk_mul_f32 v[42:43], v[42:43], v[176:177] op_sel_hi:[1,0]
	v_pk_mul_f32 v[40:41], v[40:41], v[176:177] op_sel_hi:[1,0]
	v_pk_mul_f32 v[38:39], v[38:39], v[176:177] op_sel_hi:[1,0]
	v_pk_mul_f32 v[36:37], v[36:37], v[176:177] op_sel_hi:[1,0]
	v_pk_mul_f32 v[34:35], v[34:35], v[176:177] op_sel_hi:[1,0]
	v_pk_mul_f32 v[32:33], v[32:33], v[176:177] op_sel_hi:[1,0]
	v_pk_mul_f32 v[30:31], v[30:31], v[176:177] op_sel_hi:[1,0]
	v_pk_mul_f32 v[28:29], v[28:29], v[176:177] op_sel_hi:[1,0]
	v_pk_mul_f32 v[26:27], v[26:27], v[176:177] op_sel_hi:[1,0]
	v_pk_mul_f32 v[24:25], v[24:25], v[176:177] op_sel_hi:[1,0]
	v_pk_mul_f32 v[22:23], v[22:23], v[176:177] op_sel_hi:[1,0]
	v_pk_mul_f32 v[20:21], v[20:21], v[176:177] op_sel_hi:[1,0]
	v_pk_mul_f32 v[18:19], v[18:19], v[176:177] op_sel_hi:[1,0]
	v_pk_mul_f32 v[16:17], v[16:17], v[176:177] op_sel_hi:[1,0]
	v_pk_mul_f32 v[14:15], v[14:15], v[176:177] op_sel_hi:[1,0]
	v_pk_mul_f32 v[12:13], v[12:13], v[176:177] op_sel_hi:[1,0]
	v_pk_mul_f32 v[10:11], v[10:11], v[176:177] op_sel_hi:[1,0]
	v_pk_mul_f32 v[8:9], v[8:9], v[176:177] op_sel_hi:[1,0]
	v_pk_mul_f32 v[6:7], v[6:7], v[176:177] op_sel_hi:[1,0]
	v_pk_mul_f32 v[4:5], v[4:5], v[176:177] op_sel_hi:[1,0]
	v_pk_mul_f32 v[2:3], v[2:3], v[176:177] op_sel_hi:[1,0]
	v_pk_mul_f32 v[0:1], v[0:1], v[176:177] op_sel_hi:[1,0]
	v_pk_mul_f32 v[62:63], v[62:63], v[176:177] op_sel_hi:[1,0]
	v_pk_mul_f32 v[60:61], v[60:61], v[176:177] op_sel_hi:[1,0]
	v_pk_mul_f32 v[58:59], v[58:59], v[176:177] op_sel_hi:[1,0]
	v_pk_mul_f32 v[56:57], v[56:57], v[176:177] op_sel_hi:[1,0]
	v_pk_mul_f32 v[54:55], v[54:55], v[176:177] op_sel_hi:[1,0]
	v_pk_mul_f32 v[52:53], v[52:53], v[176:177] op_sel_hi:[1,0]
	v_pk_mul_f32 v[50:51], v[50:51], v[176:177] op_sel_hi:[1,0]
	v_pk_mul_f32 v[48:49], v[48:49], v[176:177] op_sel_hi:[1,0]
	v_mul_f32_e32 v172, v172, v176
	s_branch .Latt_af0_exp
.Lba_a1:
	s_lshl_b32 s68, s65, 8
	s_addk_i32 s68, 0xfd00
	s_waitcnt lgkmcnt(0)
	v_add_u32_e32 v205, s68, v204
	v_add_u32_e32 v176, 0x17d00, v205
	v_add_u32_e32 v178, 0x17d80, v205
	ds_read2_b32 v[176:177], v176 offset1:1
	ds_read2_b32 v[178:179], v178 offset1:1
	v_add_u32_e32 v180, 0x17d08, v205
	v_add_u32_e32 v182, 0x17d88, v205
	v_add_u32_e32 v184, 0x17d20, v205
	v_add_u32_e32 v186, 0x17da0, v205
	v_add_u32_e32 v188, 0x17d28, v205
	v_add_u32_e32 v190, 0x17da8, v205
	v_add_u32_e32 v206, 0x17d40, v205
	v_add_u32_e32 v210, 0x17dc0, v205
	v_add_u32_e32 v212, 0x17d48, v205
	v_add_u32_e32 v221, 0x17dc8, v205
	ds_read2_b32 v[180:181], v180 offset1:1
	ds_read2_b32 v[182:183], v182 offset1:1
	ds_read2_b32 v[184:185], v184 offset1:1
	ds_read2_b32 v[186:187], v186 offset1:1
	ds_read2_b32 v[188:189], v188 offset1:1
	ds_read2_b32 v[190:191], v190 offset1:1
	ds_read2_b32 v[206:207], v206 offset1:1
	ds_read2_b32 v[210:211], v210 offset1:1
	ds_read2_b32 v[212:213], v212 offset1:1
	ds_read2_b32 v[224:225], v221 offset1:1
	v_add_u32_e32 v221, 0x17d60, v205
	v_add_u32_e32 v223, 0x17de0, v205
	ds_read2_b32 v[226:227], v221 offset1:1
	ds_read2_b32 v[228:229], v223 offset1:1
	v_add_u32_e32 v221, 0x17d68, v205
	v_add_u32_e32 v205, 0x17de8, v205
	ds_read2_b32 v[230:231], v221 offset1:1
	s_waitcnt lgkmcnt(14)
	v_pk_add_f32 v[96:97], v[96:97], v[176:177]
	ds_read2_b32 v[176:177], v205 offset1:1
	s_waitcnt lgkmcnt(3)
	v_pk_add_f32 v[108:109], v[108:109], v[226:227]
	v_pk_add_f32 v[106:107], v[106:107], v[212:213]
	s_waitcnt lgkmcnt(1)
	v_pk_add_f32 v[110:111], v[110:111], v[230:231]
	v_pk_add_f32 v[104:105], v[104:105], v[206:207]
	v_pk_add_f32 v[102:103], v[102:103], v[188:189]
	v_pk_add_f32 v[100:101], v[100:101], v[184:185]
	v_pk_add_f32 v[98:99], v[98:99], v[180:181]
	s_waitcnt lgkmcnt(0)
	v_pk_add_f32 v[94:95], v[94:95], v[176:177]
	v_pk_add_f32 v[92:93], v[92:93], v[228:229]
	v_pk_add_f32 v[90:91], v[90:91], v[224:225]
	v_pk_add_f32 v[88:89], v[88:89], v[210:211]
	v_pk_add_f32 v[86:87], v[86:87], v[190:191]
	v_pk_add_f32 v[84:85], v[84:85], v[186:187]
	v_pk_add_f32 v[82:83], v[82:83], v[182:183]
	v_pk_add_f32 v[80:81], v[80:81], v[178:179]
	s_nop 0
	s_branch .Latt_a1_stg

.LA0_exit:
	s_mov_b32 s69, 0
	s_branch .LBB0_243
.Lisl_597:
	s_branch .LBB0_597
.Lisl_10:
	s_branch .LBB0_10
.Lisl_11:
	s_branch .LBB0_11
.LBB0_243:
	s_and_b64 vcc, exec, s[16:17]
	s_cbranch_vccz .LBB0_245
	s_mul_i32 s4, s69, 0x5000
	v_add_u32_e32 v96, s4, v165
	ds_read_b64_tr_b16 v[64:65], v96 offset:34816
	ds_read_b64_tr_b16 v[66:67], v96 offset:37376
	ds_read_b64_tr_b16 v[68:69], v96 offset:39936
	ds_read_b64_tr_b16 v[70:71], v96 offset:42496
	ds_read_b64_tr_b16 v[72:73], v96 offset:45056
	ds_read_b64_tr_b16 v[74:75], v96 offset:47616
	ds_read_b64_tr_b16 v[76:77], v96 offset:50176
	ds_read_b64_tr_b16 v[78:79], v96 offset:52736
	s_setprio 1
	s_waitcnt lgkmcnt(6)
	v_mfma_f32_32x32x16_bf16 v[32:47], v[64:67], v[80:83], v[32:47]
	s_setprio 0
	ds_read_b64_tr_b16 v[64:65], v96 offset:34880
	ds_read_b64_tr_b16 v[66:67], v96 offset:37440
	s_setprio 1
	s_waitcnt lgkmcnt(6)
	v_mfma_f32_32x32x16_bf16 v[32:47], v[68:71], v[84:87], v[32:47]
	s_setprio 0
	ds_read_b64_tr_b16 v[68:69], v96 offset:40000
	ds_read_b64_tr_b16 v[70:71], v96 offset:42560
	s_setprio 1
	s_waitcnt lgkmcnt(6)
	v_mfma_f32_32x32x16_bf16 v[32:47], v[72:75], v[88:91], v[32:47]
	s_setprio 0
	ds_read_b64_tr_b16 v[72:73], v96 offset:45120
	ds_read_b64_tr_b16 v[74:75], v96 offset:47680
	s_setprio 1
	s_waitcnt lgkmcnt(6)
	v_mfma_f32_32x32x16_bf16 v[32:47], v[76:79], v[92:95], v[32:47]
	s_setprio 0
	ds_read_b64_tr_b16 v[76:77], v96 offset:50240
	ds_read_b64_tr_b16 v[78:79], v96 offset:52800
	s_setprio 1
	s_waitcnt lgkmcnt(6)
	v_mfma_f32_32x32x16_bf16 v[16:31], v[64:67], v[80:83], v[16:31]
	s_setprio 0
	ds_read_b64_tr_b16 v[64:65], v96 offset:34944
	ds_read_b64_tr_b16 v[66:67], v96 offset:37504
	s_setprio 1
	s_waitcnt lgkmcnt(6)
	v_mfma_f32_32x32x16_bf16 v[16:31], v[68:71], v[84:87], v[16:31]
	s_setprio 0
	ds_read_b64_tr_b16 v[68:69], v96 offset:40064
	ds_read_b64_tr_b16 v[70:71], v96 offset:42624
	s_setprio 1
	s_waitcnt lgkmcnt(6)
	v_mfma_f32_32x32x16_bf16 v[16:31], v[72:75], v[88:91], v[16:31]
	s_setprio 0
	ds_read_b64_tr_b16 v[72:73], v96 offset:45184
	ds_read_b64_tr_b16 v[74:75], v96 offset:47744
	s_setprio 1
	s_waitcnt lgkmcnt(6)
	v_mfma_f32_32x32x16_bf16 v[16:31], v[76:79], v[92:95], v[16:31]
	s_setprio 0
	ds_read_b64_tr_b16 v[76:77], v96 offset:50304
	ds_read_b64_tr_b16 v[78:79], v96 offset:52864
	s_setprio 1
	s_waitcnt lgkmcnt(6)
	v_mfma_f32_32x32x16_bf16 v[0:15], v[64:67], v[80:83], v[0:15]
	s_setprio 0
	ds_read_b64_tr_b16 v[64:65], v96 offset:35008
	ds_read_b64_tr_b16 v[66:67], v96 offset:37568
	s_setprio 1
	s_waitcnt lgkmcnt(6)
	v_mfma_f32_32x32x16_bf16 v[0:15], v[68:71], v[84:87], v[0:15]
	s_setprio 0
	ds_read_b64_tr_b16 v[68:69], v96 offset:40128
	ds_read_b64_tr_b16 v[70:71], v96 offset:42688
	s_setprio 1
	s_waitcnt lgkmcnt(6)
	v_mfma_f32_32x32x16_bf16 v[0:15], v[72:75], v[88:91], v[0:15]
	s_setprio 0
	ds_read_b64_tr_b16 v[72:73], v96 offset:45248
	ds_read_b64_tr_b16 v[74:75], v96 offset:47808
	s_setprio 1
	s_waitcnt lgkmcnt(6)
	v_mfma_f32_32x32x16_bf16 v[0:15], v[76:79], v[92:95], v[0:15]
	s_setprio 0
	ds_read_b64_tr_b16 v[76:77], v96 offset:50368
	ds_read_b64_tr_b16 v[78:79], v96 offset:52928
	s_setprio 1
	s_waitcnt lgkmcnt(6)
	v_mfma_f32_32x32x16_bf16 v[48:63], v[64:67], v[80:83], v[48:63]
	s_setprio 0
	s_setprio 1
	s_waitcnt lgkmcnt(4)
	v_mfma_f32_32x32x16_bf16 v[48:63], v[68:71], v[84:87], v[48:63]
	s_setprio 0
	s_setprio 1
	s_waitcnt lgkmcnt(2)
	v_mfma_f32_32x32x16_bf16 v[48:63], v[72:75], v[88:91], v[48:63]
	s_setprio 0
	s_setprio 1
	s_waitcnt lgkmcnt(0)
	v_mfma_f32_32x32x16_bf16 v[48:63], v[76:79], v[92:95], v[48:63]
	s_setprio 0
